# skip the per-unit next-unit row-scale reload/reduce when the next unit has the same row tile (run-time compare nxt.pm == cur.pm) in the up/a_in/kv/qg GEMM epilogues
# speedup vs baseline: 1.0256x; 1.0196x over previous
.LBB0_217:
	s_lshl_b32 s95, s24, 8
	v_cndmask_b32_e64 v136, 0, 1, s[10:11]
	s_or_b32 s81, s95, 16
	s_or_b32 s25, s95, 32
	s_or_b32 s23, s95, 48
	v_mov_b32_e32 v164, 0
	v_cmp_ne_u32_e64 s[8:9], 1, v136
	s_andn2_b64 vcc, exec, s[10:11]
	v_mov_b32_e32 v165, 0
	v_mov_b32_e32 v166, 0
	v_mov_b32_e32 v167, 0
	v_mov_b32_e32 v168, 0
	v_mov_b32_e32 v169, 0
	v_mov_b32_e32 v170, 0
	v_mov_b32_e32 v171, 0
	v_mov_b32_e32 v156, 0
	v_mov_b32_e32 v157, 0
	v_mov_b32_e32 v158, 0
	v_mov_b32_e32 v159, 0
	v_mov_b32_e32 v160, 0
	v_mov_b32_e32 v161, 0
	v_mov_b32_e32 v162, 0
	v_mov_b32_e32 v163, 0
	v_mov_b32_e32 v148, 0
	v_mov_b32_e32 v149, 0
	v_mov_b32_e32 v150, 0
	v_mov_b32_e32 v151, 0
	v_mov_b32_e32 v152, 0
	v_mov_b32_e32 v153, 0
	v_mov_b32_e32 v154, 0
	v_mov_b32_e32 v155, 0
	v_mov_b32_e32 v136, 0
	v_mov_b32_e32 v137, 0
	v_mov_b32_e32 v138, 0
	v_mov_b32_e32 v139, 0
	v_mov_b32_e32 v144, 0
	v_mov_b32_e32 v145, 0
	v_mov_b32_e32 v146, 0
	v_mov_b32_e32 v147, 0
	s_cbranch_vccnz .LBB0_219
	s_cmp_eq_u32 s24, s85
	s_cbranch_scc1 .LBB0_219
	v_add_u32_e32 v136, s95, v226
	v_ashrrev_i32_e32 v137, 31, v136
	v_lshlrev_b64 v[136:137], 7, v[136:137]
	v_lshl_add_u64 v[136:137], v[178:179], 0, v[136:137]
	global_load_dwordx4 v[164:167], v[136:137], off
	global_load_dwordx4 v[168:171], v[136:137], off offset:16
	v_add_u32_e32 v136, s81, v226
	v_ashrrev_i32_e32 v137, 31, v136
	v_lshlrev_b64 v[136:137], 7, v[136:137]
	v_lshl_add_u64 v[136:137], v[178:179], 0, v[136:137]
	global_load_dwordx4 v[156:159], v[136:137], off
	global_load_dwordx4 v[160:163], v[136:137], off offset:16
	v_add_u32_e32 v136, s25, v226
	v_ashrrev_i32_e32 v137, 31, v136
	v_lshlrev_b64 v[136:137], 7, v[136:137]
	v_lshl_add_u64 v[136:137], v[178:179], 0, v[136:137]
	global_load_dwordx4 v[148:151], v[136:137], off
	global_load_dwordx4 v[152:155], v[136:137], off offset:16
	v_add_u32_e32 v136, s23, v226
	v_ashrrev_i32_e32 v137, 31, v136
	v_lshlrev_b64 v[136:137], 7, v[136:137]
	v_lshl_add_u64 v[144:145], v[178:179], 0, v[136:137]
	global_load_dwordx4 v[136:139], v[144:145], off
	s_nop 0
	global_load_dwordx4 v[144:147], v[144:145], off offset:16

.LBB0_243:
	s_mov_b64 s[12:13], 0x3000
	v_lshl_add_u64 v[194:195], v[204:205], 0, s[12:13]
	v_cvt_pk_bf16_f32 v204, v210, v211
	v_cvt_pk_bf16_f32 v205, v206, v207
	v_cvt_pk_bf16_f32 v206, v192, v193
	v_add_co_u32_e32 v192, vcc, 0x100000, v194
	v_cvt_pk_bf16_f32 v207, v208, v209
	s_nop 1
	v_addc_co_u32_e32 v193, vcc, 0, v195, vcc
	s_and_b64 vcc, exec, s[8:9]
	global_store_dwordx4 v[192:193], v[204:207], off
	s_cbranch_vccnz .LBB0_253
	s_cmp_eq_u32 s24, s85
	s_cbranch_scc1 .LBB0_253
	s_waitcnt vmcnt(0)
	v_add_f32_e32 v164, v164, v165
	v_add_f32_e32 v165, v166, v167
	v_add_f32_e32 v164, v164, v165
	v_add_f32_e32 v165, v168, v169
	v_add_f32_e32 v166, v170, v171
	v_add_f32_e32 v165, v165, v166
	v_add_f32_e32 v164, v164, v165
	ds_bpermute_b32 v165, v227, v164
	s_waitcnt lgkmcnt(0)
	v_add_f32_e32 v164, v164, v165
	ds_bpermute_b32 v165, v228, v164
	s_and_saveexec_b64 s[36:37], s[4:5]
	s_cbranch_execz .LBB0_246
	s_waitcnt lgkmcnt(0)
	v_add_f32_e32 v164, v164, v165
	v_fmamk_f32 v164, v164, 0x3a000000, v218
	v_mul_f32_e32 v165, 0x4f800000, v164
	v_cmp_gt_f32_e32 vcc, s49, v164
	s_nop 1
	v_cndmask_b32_e32 v164, v164, v165, vcc
	v_sqrt_f32_e32 v165, v164
	s_nop 0
	v_add_u32_e32 v166, -1, v165
	v_fma_f32 v168, -v166, v165, v164
	v_add_u32_e32 v167, 1, v165
	v_cmp_ge_f32_e64 s[12:13], 0, v168
	s_nop 1
	v_cndmask_b32_e64 v166, v165, v166, s[12:13]
	v_fma_f32 v165, -v167, v165, v164
	v_cmp_lt_f32_e64 s[12:13], 0, v165
	s_nop 1
	v_cndmask_b32_e64 v165, v166, v167, s[12:13]
	v_mul_f32_e32 v166, 0x37800000, v165
	v_cndmask_b32_e32 v165, v165, v166, vcc
	v_cmp_class_f32_e32 vcc, v164, v220
	s_nop 1
	v_cndmask_b32_e32 v164, v165, v164, vcc
	v_div_scale_f32 v165, s[12:13], v164, v164, 1.0
	v_rcp_f32_e32 v166, v165
	s_nop 0
	v_fma_f32 v167, -v165, v166, 1.0
	v_fmac_f32_e32 v166, v167, v166
	v_div_scale_f32 v167, vcc, 1.0, v164, 1.0
	v_mul_f32_e32 v168, v167, v166
	v_fma_f32 v169, -v165, v168, v167
	v_fmac_f32_e32 v168, v169, v166
	v_fma_f32 v165, -v165, v168, v167
	v_div_fmas_f32 v165, v165, v166, v168
	v_div_fixup_f32 v164, v165, v164, 1.0
	ds_write_b32 v243, v164

.LBB0_277:
	s_mov_b64 s[10:11], 0x3000
	s_waitcnt vmcnt(0)
	v_lshl_add_u64 v[140:141], v[192:193], 0, s[10:11]
	v_add_co_u32_e32 v140, vcc, 0x100000, v140
	s_add_u32 s10, s67, 0xffffff00
	s_nop 0
	v_addc_co_u32_e32 v141, vcc, 0, v141, vcc
	s_addc_u32 s11, s43, -1
	s_and_b64 vcc, exec, s[8:9]
	v_cvt_pk_bf16_f32 v132, v206, v207
	v_cvt_pk_bf16_f32 v133, v194, v195
	v_cvt_pk_bf16_f32 v134, v188, v189
	v_cvt_pk_bf16_f32 v135, v204, v205
	global_store_dwordx4 v[140:141], v[132:135], off
	s_cbranch_vccnz .LBB0_288
	s_cmp_eq_u32 s24, s85
	s_cbranch_scc1 .LBB0_286
	v_add_f32_e32 v4, v164, v165
	v_add_f32_e32 v5, v166, v167
	v_add_f32_e32 v4, v4, v5
	v_add_f32_e32 v5, v168, v169
	v_add_f32_e32 v6, v170, v171
	v_add_f32_e32 v5, v5, v6
	v_add_f32_e32 v4, v4, v5
	ds_bpermute_b32 v5, v227, v4
	s_waitcnt lgkmcnt(0)
	v_add_f32_e32 v4, v4, v5
	ds_bpermute_b32 v5, v228, v4
	s_and_saveexec_b64 s[10:11], s[4:5]
	s_cbranch_execz .LBB0_280
	s_waitcnt lgkmcnt(0)
	v_add_f32_e32 v4, v4, v5
	v_fmamk_f32 v4, v4, 0x3a000000, v218
	v_mul_f32_e32 v5, 0x4f800000, v4
	v_cmp_gt_f32_e32 vcc, s49, v4
	s_nop 1
	v_cndmask_b32_e32 v4, v4, v5, vcc
	v_sqrt_f32_e32 v5, v4
	s_nop 0
	v_add_u32_e32 v6, -1, v5
	v_fma_f32 v8, -v6, v5, v4
	v_add_u32_e32 v7, 1, v5
	v_cmp_ge_f32_e64 s[8:9], 0, v8
	s_nop 1
	v_cndmask_b32_e64 v6, v5, v6, s[8:9]
	v_fma_f32 v5, -v7, v5, v4
	v_cmp_lt_f32_e64 s[8:9], 0, v5
	s_nop 1
	v_cndmask_b32_e64 v5, v6, v7, s[8:9]
	v_mul_f32_e32 v6, 0x37800000, v5
	v_cndmask_b32_e32 v5, v5, v6, vcc
	v_cmp_class_f32_e32 vcc, v4, v220
	s_nop 1
	v_cndmask_b32_e32 v4, v5, v4, vcc
	v_div_scale_f32 v5, s[8:9], v4, v4, 1.0
	v_rcp_f32_e32 v6, v5
	s_nop 0
	v_fma_f32 v7, -v5, v6, 1.0
	v_fmac_f32_e32 v6, v7, v6
	v_div_scale_f32 v7, vcc, 1.0, v4, 1.0
	v_mul_f32_e32 v8, v7, v6
	v_fma_f32 v9, -v5, v8, v7
	v_fmac_f32_e32 v8, v9, v6
	v_fma_f32 v5, -v5, v8, v7
	v_div_fmas_f32 v5, v5, v6, v8
	v_div_fixup_f32 v4, v5, v4, 1.0
	ds_write_b32 v243, v4 offset:256

.LBB0_356:
	s_lshl_b32 s66, s26, 8
	v_cndmask_b32_e64 v132, 0, 1, s[10:11]
	s_or_b32 s43, s66, 16
	s_or_b32 s27, s66, 32
	s_or_b32 s25, s66, 48
	v_mov_b32_e32 v164, 0
	v_cmp_ne_u32_e64 s[8:9], 1, v132
	s_andn2_b64 vcc, exec, s[10:11]
	v_mov_b32_e32 v165, 0
	v_mov_b32_e32 v166, 0
	v_mov_b32_e32 v167, 0
	v_mov_b32_e32 v168, 0
	v_mov_b32_e32 v169, 0
	v_mov_b32_e32 v170, 0
	v_mov_b32_e32 v171, 0
	v_mov_b32_e32 v156, 0
	v_mov_b32_e32 v157, 0
	v_mov_b32_e32 v158, 0
	v_mov_b32_e32 v159, 0
	v_mov_b32_e32 v160, 0
	v_mov_b32_e32 v161, 0
	v_mov_b32_e32 v162, 0
	v_mov_b32_e32 v163, 0
	v_mov_b32_e32 v148, 0
	v_mov_b32_e32 v149, 0
	v_mov_b32_e32 v150, 0
	v_mov_b32_e32 v151, 0
	v_mov_b32_e32 v152, 0
	v_mov_b32_e32 v153, 0
	v_mov_b32_e32 v154, 0
	v_mov_b32_e32 v155, 0
	v_mov_b32_e32 v132, 0
	s_waitcnt lgkmcnt(0)
	v_mov_b32_e32 v133, 0
	v_mov_b32_e32 v134, 0
	v_mov_b32_e32 v135, 0
	v_mov_b32_e32 v136, 0
	v_mov_b32_e32 v137, 0
	v_mov_b32_e32 v138, 0
	v_mov_b32_e32 v139, 0
	s_cbranch_vccnz .LBB0_358
	s_cmp_eq_u32 s26, s74
	s_cbranch_scc1 .LBB0_358
	v_add_u32_e32 v132, s66, v3
	v_ashrrev_i32_e32 v133, 31, v132
	v_lshlrev_b64 v[132:133], 7, v[132:133]
	v_lshl_add_u64 v[132:133], v[178:179], 0, v[132:133]
	global_load_dwordx4 v[164:167], v[132:133], off
	global_load_dwordx4 v[168:171], v[132:133], off offset:16
	v_add_u32_e32 v132, s43, v3
	v_ashrrev_i32_e32 v133, 31, v132
	v_lshlrev_b64 v[132:133], 7, v[132:133]
	v_lshl_add_u64 v[132:133], v[178:179], 0, v[132:133]
	global_load_dwordx4 v[156:159], v[132:133], off
	global_load_dwordx4 v[160:163], v[132:133], off offset:16
	v_add_u32_e32 v132, s27, v3
	v_ashrrev_i32_e32 v133, 31, v132
	v_lshlrev_b64 v[132:133], 7, v[132:133]
	v_lshl_add_u64 v[132:133], v[178:179], 0, v[132:133]
	global_load_dwordx4 v[148:151], v[132:133], off
	global_load_dwordx4 v[152:155], v[132:133], off offset:16
	v_add_u32_e32 v132, s25, v3
	v_ashrrev_i32_e32 v133, 31, v132
	v_lshlrev_b64 v[132:133], 7, v[132:133]
	v_lshl_add_u64 v[136:137], v[178:179], 0, v[132:133]
	global_load_dwordx4 v[132:135], v[136:137], off
	s_nop 0
	global_load_dwordx4 v[136:139], v[136:137], off offset:16

.LBB0_398:
	s_and_b64 vcc, exec, s[8:9]
	v_cvt_pk_bf16_f32 v212, v212, v213
	v_cvt_pk_bf16_f32 v213, v208, v209
	v_cvt_pk_bf16_f32 v214, v194, v195
	v_cvt_pk_bf16_f32 v215, v210, v211
	global_store_dwordx4 v[206:207], v[212:215], off offset:256
	s_cbranch_vccnz .LBB0_408
	s_cmp_eq_u32 s26, s74
	s_cbranch_scc1 .LBB0_408
	s_waitcnt vmcnt(0)
	v_add_f32_e32 v164, v164, v165
	v_add_f32_e32 v165, v166, v167
	v_add_f32_e32 v164, v164, v165
	v_add_f32_e32 v165, v168, v169
	v_add_f32_e32 v166, v170, v171
	v_add_f32_e32 v165, v165, v166
	v_add_f32_e32 v164, v164, v165
	ds_bpermute_b32 v165, v226, v164
	s_waitcnt lgkmcnt(0)
	v_add_f32_e32 v164, v164, v165
	ds_bpermute_b32 v165, v227, v164
	s_and_saveexec_b64 s[36:37], s[4:5]
	s_cbranch_execz .LBB0_401
	s_waitcnt lgkmcnt(0)
	v_add_f32_e32 v164, v164, v165
	v_fmamk_f32 v164, v164, 0x3a000000, v218
	v_mul_f32_e32 v165, 0x4f800000, v164
	v_cmp_gt_f32_e32 vcc, s49, v164
	s_nop 1
	v_cndmask_b32_e32 v164, v164, v165, vcc
	v_sqrt_f32_e32 v165, v164
	s_nop 0
	v_add_u32_e32 v166, -1, v165
	v_fma_f32 v168, -v166, v165, v164
	v_add_u32_e32 v167, 1, v165
	v_cmp_ge_f32_e64 s[16:17], 0, v168
	s_nop 1
	v_cndmask_b32_e64 v166, v165, v166, s[16:17]
	v_fma_f32 v165, -v167, v165, v164
	v_cmp_lt_f32_e64 s[16:17], 0, v165
	s_nop 1
	v_cndmask_b32_e64 v165, v166, v167, s[16:17]
	v_mul_f32_e32 v166, 0x37800000, v165
	v_cndmask_b32_e32 v165, v165, v166, vcc
	v_cmp_class_f32_e32 vcc, v164, v220
	s_nop 1
	v_cndmask_b32_e32 v164, v165, v164, vcc
	v_div_scale_f32 v165, s[16:17], v164, v164, 1.0
	v_rcp_f32_e32 v166, v165
	s_nop 0
	v_fma_f32 v167, -v165, v166, 1.0
	v_fmac_f32_e32 v166, v167, v166
	v_div_scale_f32 v167, vcc, 1.0, v164, 1.0
	v_mul_f32_e32 v168, v167, v166
	v_fma_f32 v169, -v165, v168, v167
	v_fmac_f32_e32 v168, v169, v166
	v_fma_f32 v165, -v165, v168, v167
	v_div_fmas_f32 v165, v165, v166, v168
	v_div_fixup_f32 v164, v165, v164, 1.0
	ds_write_b32 v243, v164

.LBB0_448:
	s_mov_b64 s[10:11], 0x160000
	s_waitcnt vmcnt(0)
	v_lshl_add_u64 v[144:145], v[190:191], 0, s[10:11]
	s_add_u32 s10, s92, 0xffffff00
	s_addc_u32 s11, s93, -1
	s_and_b64 vcc, exec, s[8:9]
	v_cvt_pk_bf16_f32 v140, v204, v205
	v_cvt_pk_bf16_f32 v141, v192, v193
	v_cvt_pk_bf16_f32 v142, v186, v187
	v_cvt_pk_bf16_f32 v143, v194, v195
	global_store_dwordx4 v[144:145], v[140:143], off offset:256
	s_cbranch_vccnz .LBB0_459
	s_cmp_eq_u32 s26, s74
	s_cbranch_scc1 .LBB0_457
	v_add_f32_e32 v4, v164, v165
	v_add_f32_e32 v5, v166, v167
	v_add_f32_e32 v4, v4, v5
	v_add_f32_e32 v5, v168, v169
	v_add_f32_e32 v6, v170, v171
	v_add_f32_e32 v5, v5, v6
	v_add_f32_e32 v4, v4, v5
	ds_bpermute_b32 v5, v226, v4
	s_waitcnt lgkmcnt(0)
	v_add_f32_e32 v4, v4, v5
	ds_bpermute_b32 v5, v227, v4
	s_and_saveexec_b64 s[10:11], s[4:5]
	s_cbranch_execz .LBB0_451
	s_waitcnt lgkmcnt(0)
	v_add_f32_e32 v4, v4, v5
	v_fmamk_f32 v4, v4, 0x3a000000, v218
	v_mul_f32_e32 v5, 0x4f800000, v4
	v_cmp_gt_f32_e32 vcc, s49, v4
	s_nop 1
	v_cndmask_b32_e32 v4, v4, v5, vcc
	v_sqrt_f32_e32 v5, v4
	s_nop 0
	v_add_u32_e32 v6, -1, v5
	v_fma_f32 v8, -v6, v5, v4
	v_add_u32_e32 v7, 1, v5
	v_cmp_ge_f32_e64 s[8:9], 0, v8
	s_nop 1
	v_cndmask_b32_e64 v6, v5, v6, s[8:9]
	v_fma_f32 v5, -v7, v5, v4
	v_cmp_lt_f32_e64 s[8:9], 0, v5
	s_nop 1
	v_cndmask_b32_e64 v5, v6, v7, s[8:9]
	v_mul_f32_e32 v6, 0x37800000, v5
	v_cndmask_b32_e32 v5, v5, v6, vcc
	v_cmp_class_f32_e32 vcc, v4, v220
	s_nop 1
	v_cndmask_b32_e32 v4, v5, v4, vcc
	v_div_scale_f32 v5, s[8:9], v4, v4, 1.0
	v_rcp_f32_e32 v6, v5
	s_nop 0
	v_fma_f32 v7, -v5, v6, 1.0
	v_fmac_f32_e32 v6, v7, v6
	v_div_scale_f32 v7, vcc, 1.0, v4, 1.0
	v_mul_f32_e32 v8, v7, v6
	v_fma_f32 v9, -v5, v8, v7
	v_fmac_f32_e32 v8, v9, v6
	v_fma_f32 v5, -v5, v8, v7
	v_div_fmas_f32 v5, v5, v6, v8
	v_div_fixup_f32 v4, v5, v4, 1.0
	ds_write_b32 v243, v4 offset:256

.LBB0_806:
	v_add_u32_e32 v211, s93, v206
	ds_read2_b32 v[186:187], v211 offset1:16
	ds_read2_b32 v[184:185], v211 offset0:32 offset1:48
	ds_read2_b32 v[182:183], v211 offset0:64 offset1:80
	ds_read2_b32 v[176:177], v211 offset0:96 offset1:112
	s_waitcnt lgkmcnt(0)
	s_lshl_b32 s81, s26, 8
	v_cndmask_b32_e64 v132, 0, 1, s[10:11]
	s_or_b32 s43, s81, 16
	s_or_b32 s27, s81, 32
	s_or_b32 s25, s81, 48
	v_mov_b32_e32 v156, 0
	v_cmp_ne_u32_e64 s[8:9], 1, v132
	s_andn2_b64 vcc, exec, s[10:11]
	v_mov_b32_e32 v157, 0
	v_mov_b32_e32 v158, 0
	v_mov_b32_e32 v159, 0
	v_mov_b32_e32 v160, 0
	v_mov_b32_e32 v161, 0
	v_mov_b32_e32 v162, 0
	v_mov_b32_e32 v163, 0
	v_mov_b32_e32 v148, 0
	v_mov_b32_e32 v149, 0
	v_mov_b32_e32 v150, 0
	v_mov_b32_e32 v151, 0
	v_mov_b32_e32 v152, 0
	v_mov_b32_e32 v153, 0
	v_mov_b32_e32 v154, 0
	v_mov_b32_e32 v155, 0
	v_mov_b32_e32 v140, 0
	v_mov_b32_e32 v141, 0
	v_mov_b32_e32 v142, 0
	v_mov_b32_e32 v143, 0
	v_mov_b32_e32 v144, 0
	v_mov_b32_e32 v145, 0
	v_mov_b32_e32 v146, 0
	v_mov_b32_e32 v147, 0
	v_mov_b32_e32 v132, 0
	v_mov_b32_e32 v133, 0
	v_mov_b32_e32 v134, 0
	v_mov_b32_e32 v135, 0
	v_mov_b32_e32 v136, 0
	v_mov_b32_e32 v137, 0
	v_mov_b32_e32 v138, 0
	v_mov_b32_e32 v139, 0
	s_cbranch_vccnz .LBB0_808
	s_cmp_eq_u32 s26, s3
	s_cbranch_scc1 .LBB0_808
	v_add_u32_e32 v132, s81, v3
	v_ashrrev_i32_e32 v133, 31, v132
	v_lshlrev_b64 v[132:133], 7, v[132:133]
	v_lshl_add_u64 v[132:133], v[170:171], 0, v[132:133]
	global_load_dwordx4 v[156:159], v[132:133], off
	global_load_dwordx4 v[160:163], v[132:133], off offset:16
	v_add_u32_e32 v132, s43, v3
	v_ashrrev_i32_e32 v133, 31, v132
	v_lshlrev_b64 v[132:133], 7, v[132:133]
	v_lshl_add_u64 v[132:133], v[170:171], 0, v[132:133]
	global_load_dwordx4 v[148:151], v[132:133], off
	global_load_dwordx4 v[152:155], v[132:133], off offset:16
	v_add_u32_e32 v132, s27, v3
	v_ashrrev_i32_e32 v133, 31, v132
	v_lshlrev_b64 v[132:133], 7, v[132:133]
	v_lshl_add_u64 v[132:133], v[170:171], 0, v[132:133]
	global_load_dwordx4 v[140:143], v[132:133], off
	global_load_dwordx4 v[144:147], v[132:133], off offset:16
	v_add_u32_e32 v132, s25, v3
	v_ashrrev_i32_e32 v133, 31, v132
	v_lshlrev_b64 v[132:133], 7, v[132:133]
	v_lshl_add_u64 v[136:137], v[170:171], 0, v[132:133]
	global_load_dwordx4 v[132:135], v[136:137], off
	s_nop 0
	global_load_dwordx4 v[136:139], v[136:137], off offset:16

.LBB0_824:
	s_and_b64 vcc, exec, s[8:9]
	s_cbranch_vccnz .LBB0_834
	s_cmp_eq_u32 s26, s3
	s_cbranch_scc1 .LBB0_834
	s_waitcnt vmcnt(0)
	v_add_f32_e32 v156, v156, v157
	v_add_f32_e32 v157, v158, v159
	v_add_f32_e32 v156, v156, v157
	v_add_f32_e32 v157, v160, v161
	v_add_f32_e32 v158, v162, v163
	v_add_f32_e32 v157, v157, v158
	v_add_f32_e32 v156, v156, v157
	ds_bpermute_b32 v157, v204, v156
	s_waitcnt lgkmcnt(0)
	v_add_f32_e32 v156, v156, v157
	ds_bpermute_b32 v157, v205, v156
	s_and_saveexec_b64 s[36:37], s[4:5]
	s_cbranch_execz .LBB0_827
	s_waitcnt lgkmcnt(0)
	v_add_f32_e32 v156, v156, v157
	v_fmamk_f32 v156, v156, 0x3a000000, v218
	v_mul_f32_e32 v157, 0x4f800000, v156
	v_cmp_gt_f32_e32 vcc, s49, v156
	s_nop 1
	v_cndmask_b32_e32 v156, v156, v157, vcc
	v_sqrt_f32_e32 v157, v156
	s_nop 0
	v_add_u32_e32 v158, -1, v157
	v_fma_f32 v160, -v158, v157, v156
	v_add_u32_e32 v159, 1, v157
	v_cmp_ge_f32_e64 s[12:13], 0, v160
	s_nop 1
	v_cndmask_b32_e64 v158, v157, v158, s[12:13]
	v_fma_f32 v157, -v159, v157, v156
	v_cmp_lt_f32_e64 s[12:13], 0, v157
	s_nop 1
	v_cndmask_b32_e64 v157, v158, v159, s[12:13]
	v_mul_f32_e32 v158, 0x37800000, v157
	v_cndmask_b32_e32 v157, v157, v158, vcc
	v_cmp_class_f32_e32 vcc, v156, v220
	s_nop 1
	v_cndmask_b32_e32 v156, v157, v156, vcc
	v_div_scale_f32 v157, s[12:13], v156, v156, 1.0
	v_rcp_f32_e32 v158, v157
	s_nop 0
	v_fma_f32 v159, -v157, v158, 1.0
	v_fmac_f32_e32 v158, v159, v158
	v_div_scale_f32 v159, vcc, 1.0, v156, 1.0
	v_mul_f32_e32 v160, v159, v158
	v_fma_f32 v161, -v157, v160, v159
	v_fmac_f32_e32 v160, v161, v158
	v_fma_f32 v157, -v157, v160, v159
	v_div_fmas_f32 v157, v157, v158, v160
	v_div_fixup_f32 v156, v157, v156, 1.0
	ds_write_b32 v211, v156

.LBB0_850:
	s_add_u32 s10, s84, 0xffffff00
	s_addc_u32 s11, s85, -1
	s_and_b64 vcc, exec, s[8:9]
	s_cbranch_vccnz .LBB0_861
	s_cmp_eq_u32 s26, s3
	s_cbranch_scc1 .LBB0_859
	s_waitcnt vmcnt(0)
	v_add_f32_e32 v4, v156, v157
	v_add_f32_e32 v5, v158, v159
	v_add_f32_e32 v4, v4, v5
	v_add_f32_e32 v5, v160, v161
	v_add_f32_e32 v6, v162, v163
	v_add_f32_e32 v5, v5, v6
	v_add_f32_e32 v4, v4, v5
	ds_bpermute_b32 v5, v204, v4
	s_waitcnt lgkmcnt(0)
	v_add_f32_e32 v4, v4, v5
	ds_bpermute_b32 v5, v205, v4
	s_and_saveexec_b64 s[10:11], s[4:5]
	s_cbranch_execz .LBB0_853
	s_waitcnt lgkmcnt(0)
	v_add_f32_e32 v4, v4, v5
	v_fmamk_f32 v4, v4, 0x3a000000, v218
	v_mul_f32_e32 v5, 0x4f800000, v4
	v_cmp_gt_f32_e32 vcc, s49, v4
	s_nop 1
	v_cndmask_b32_e32 v4, v4, v5, vcc
	v_sqrt_f32_e32 v5, v4
	s_nop 0
	v_add_u32_e32 v6, -1, v5
	v_fma_f32 v8, -v6, v5, v4
	v_add_u32_e32 v7, 1, v5
	v_cmp_ge_f32_e64 s[8:9], 0, v8
	s_nop 1
	v_cndmask_b32_e64 v6, v5, v6, s[8:9]
	v_fma_f32 v5, -v7, v5, v4
	v_cmp_lt_f32_e64 s[8:9], 0, v5
	s_nop 1
	v_cndmask_b32_e64 v5, v6, v7, s[8:9]
	v_mul_f32_e32 v6, 0x37800000, v5
	v_cndmask_b32_e32 v5, v5, v6, vcc
	v_cmp_class_f32_e32 vcc, v4, v220
	s_nop 1
	v_cndmask_b32_e32 v4, v5, v4, vcc
	v_div_scale_f32 v5, s[8:9], v4, v4, 1.0
	v_rcp_f32_e32 v6, v5
	s_nop 0
	v_fma_f32 v7, -v5, v6, 1.0
	v_fmac_f32_e32 v6, v7, v6
	v_div_scale_f32 v7, vcc, 1.0, v4, 1.0
	v_mul_f32_e32 v8, v7, v6
	v_fma_f32 v9, -v5, v8, v7
	v_fmac_f32_e32 v8, v9, v6
	v_fma_f32 v5, -v5, v8, v7
	v_div_fmas_f32 v5, v5, v6, v8
	v_div_fixup_f32 v4, v5, v4, 1.0
	ds_write_b32 v211, v4 offset:256

.Lfe_join:
	s_mov_b64 exec, -1
	s_waitcnt lgkmcnt(0)
	s_barrier
	s_mov_b32 exec_lo, 0xc000c000
	s_mov_b32 exec_hi, 0xc000c000
	ds_read_b128 v[246:249], v234 offset:0
	ds_read_b128 v[250:253], v234 offset:16
	s_mov_b64 exec, -1
	s_waitcnt vmcnt(12)
	v_fma_f32 v176, v132, v108, v156
	v_fma_f32 v177, v133, v109, v157
	v_fma_f32 v178, v134, v110, v158
	v_fma_f32 v179, v135, v111, v159
	v_fma_f32 v182, v136, v104, v160
	v_fma_f32 v183, v137, v105, v161
	v_fma_f32 v184, v138, v106, v162
	v_fma_f32 v185, v139, v107, v163
	v_fmac_f32_dpp v176, v108, v140 row_shr:1 row_mask:0xf bank_mask:0xf
	v_fmac_f32_dpp v177, v109, v141 row_shr:1 row_mask:0xf bank_mask:0xf
	v_fmac_f32_dpp v178, v110, v142 row_shr:1 row_mask:0xf bank_mask:0xf
	v_fmac_f32_dpp v179, v111, v143 row_shr:1 row_mask:0xf bank_mask:0xf
	v_fmac_f32_dpp v182, v104, v144 row_shr:1 row_mask:0xf bank_mask:0xf
	v_fmac_f32_dpp v183, v105, v145 row_shr:1 row_mask:0xf bank_mask:0xf
	v_fmac_f32_dpp v184, v106, v146 row_shr:1 row_mask:0xf bank_mask:0xf
	v_fmac_f32_dpp v185, v107, v147 row_shr:1 row_mask:0xf bank_mask:0xf
	v_fmac_f32_dpp v176, v108, v148 row_shr:2 row_mask:0xf bank_mask:0xf
	v_fmac_f32_dpp v177, v109, v149 row_shr:2 row_mask:0xf bank_mask:0xf
	v_fmac_f32_dpp v178, v110, v150 row_shr:2 row_mask:0xf bank_mask:0xf
	v_fmac_f32_dpp v179, v111, v151 row_shr:2 row_mask:0xf bank_mask:0xf
	v_fmac_f32_dpp v182, v104, v152 row_shr:2 row_mask:0xf bank_mask:0xf
	v_fmac_f32_dpp v183, v105, v153 row_shr:2 row_mask:0xf bank_mask:0xf
	v_fmac_f32_dpp v184, v106, v154 row_shr:2 row_mask:0xf bank_mask:0xf
	v_fmac_f32_dpp v185, v107, v155 row_shr:2 row_mask:0xf bank_mask:0xf
	v_fmac_f32_dpp v176, v116, v140 row_shl:15 row_mask:0xf bank_mask:0xf
	v_fmac_f32_dpp v177, v117, v141 row_shl:15 row_mask:0xf bank_mask:0xf
	v_fmac_f32_dpp v178, v118, v142 row_shl:15 row_mask:0xf bank_mask:0xf
	v_fmac_f32_dpp v179, v119, v143 row_shl:15 row_mask:0xf bank_mask:0xf
	v_fmac_f32_dpp v182, v112, v144 row_shl:15 row_mask:0xf bank_mask:0xf
	v_fmac_f32_dpp v183, v113, v145 row_shl:15 row_mask:0xf bank_mask:0xf
	v_fmac_f32_dpp v184, v114, v146 row_shl:15 row_mask:0xf bank_mask:0xf
	v_fmac_f32_dpp v185, v115, v147 row_shl:15 row_mask:0xf bank_mask:0xf
	v_fmac_f32_dpp v176, v116, v148 row_shl:14 row_mask:0xf bank_mask:0xf
	v_fmac_f32_dpp v177, v117, v149 row_shl:14 row_mask:0xf bank_mask:0xf
	v_fmac_f32_dpp v178, v118, v150 row_shl:14 row_mask:0xf bank_mask:0xf
	v_fmac_f32_dpp v179, v119, v151 row_shl:14 row_mask:0xf bank_mask:0xf
	v_fmac_f32_dpp v182, v112, v152 row_shl:14 row_mask:0xf bank_mask:0xf
	v_fmac_f32_dpp v183, v113, v153 row_shl:14 row_mask:0xf bank_mask:0xf
	v_fmac_f32_dpp v184, v114, v154 row_shl:14 row_mask:0xf bank_mask:0xf
	v_fmac_f32_dpp v185, v115, v155 row_shl:14 row_mask:0xf bank_mask:0xf
	v_fma_f32 v108, v132, v116, v156
	v_fma_f32 v109, v133, v117, v157
	v_fma_f32 v110, v134, v118, v158
	v_fma_f32 v111, v135, v119, v159
	v_fma_f32 v104, v136, v112, v160
	v_fma_f32 v105, v137, v113, v161
	v_fma_f32 v106, v138, v114, v162
	v_fma_f32 v107, v139, v115, v163
	v_fmac_f32_dpp v108, v116, v140 row_shr:1 row_mask:0xf bank_mask:0xf
	v_fmac_f32_dpp v109, v117, v141 row_shr:1 row_mask:0xf bank_mask:0xf
	v_fmac_f32_dpp v110, v118, v142 row_shr:1 row_mask:0xf bank_mask:0xf
	v_fmac_f32_dpp v111, v119, v143 row_shr:1 row_mask:0xf bank_mask:0xf
	v_fmac_f32_dpp v104, v112, v144 row_shr:1 row_mask:0xf bank_mask:0xf
	v_fmac_f32_dpp v105, v113, v145 row_shr:1 row_mask:0xf bank_mask:0xf
	v_fmac_f32_dpp v106, v114, v146 row_shr:1 row_mask:0xf bank_mask:0xf
	v_fmac_f32_dpp v107, v115, v147 row_shr:1 row_mask:0xf bank_mask:0xf
	v_fmac_f32_dpp v108, v116, v148 row_shr:2 row_mask:0xf bank_mask:0xf
	v_fmac_f32_dpp v109, v117, v149 row_shr:2 row_mask:0xf bank_mask:0xf
	v_fmac_f32_dpp v110, v118, v150 row_shr:2 row_mask:0xf bank_mask:0xf
	v_fmac_f32_dpp v111, v119, v151 row_shr:2 row_mask:0xf bank_mask:0xf
	v_fmac_f32_dpp v104, v112, v152 row_shr:2 row_mask:0xf bank_mask:0xf
	v_fmac_f32_dpp v105, v113, v153 row_shr:2 row_mask:0xf bank_mask:0xf
	v_fmac_f32_dpp v106, v114, v154 row_shr:2 row_mask:0xf bank_mask:0xf
	v_fmac_f32_dpp v107, v115, v155 row_shr:2 row_mask:0xf bank_mask:0xf
	v_fmac_f32_dpp v108, v124, v140 row_shl:15 row_mask:0xf bank_mask:0xf
	v_fmac_f32_dpp v109, v125, v141 row_shl:15 row_mask:0xf bank_mask:0xf
	v_fmac_f32_dpp v110, v126, v142 row_shl:15 row_mask:0xf bank_mask:0xf
	v_fmac_f32_dpp v111, v127, v143 row_shl:15 row_mask:0xf bank_mask:0xf
	v_fmac_f32_dpp v104, v120, v144 row_shl:15 row_mask:0xf bank_mask:0xf
	v_fmac_f32_dpp v105, v121, v145 row_shl:15 row_mask:0xf bank_mask:0xf
	v_fmac_f32_dpp v106, v122, v146 row_shl:15 row_mask:0xf bank_mask:0xf
	v_fmac_f32_dpp v107, v123, v147 row_shl:15 row_mask:0xf bank_mask:0xf
	v_fmac_f32_dpp v108, v124, v148 row_shl:14 row_mask:0xf bank_mask:0xf
	v_fmac_f32_dpp v109, v125, v149 row_shl:14 row_mask:0xf bank_mask:0xf
	v_fmac_f32_dpp v110, v126, v150 row_shl:14 row_mask:0xf bank_mask:0xf
	v_fmac_f32_dpp v111, v127, v151 row_shl:14 row_mask:0xf bank_mask:0xf
	v_fmac_f32_dpp v104, v120, v152 row_shl:14 row_mask:0xf bank_mask:0xf
	v_fmac_f32_dpp v105, v121, v153 row_shl:14 row_mask:0xf bank_mask:0xf
	v_fmac_f32_dpp v106, v122, v154 row_shl:14 row_mask:0xf bank_mask:0xf
	v_fmac_f32_dpp v107, v123, v155 row_shl:14 row_mask:0xf bank_mask:0xf
	v_fma_f32 v116, v132, v124, v156
	v_fma_f32 v117, v133, v125, v157
	v_fma_f32 v118, v134, v126, v158
	v_fma_f32 v119, v135, v127, v159
	v_fma_f32 v112, v136, v120, v160
	v_fma_f32 v113, v137, v121, v161
	v_fma_f32 v114, v138, v122, v162
	v_fma_f32 v115, v139, v123, v163
	v_fmac_f32_dpp v116, v124, v140 row_shr:1 row_mask:0xf bank_mask:0xf
	v_fmac_f32_dpp v117, v125, v141 row_shr:1 row_mask:0xf bank_mask:0xf
	v_fmac_f32_dpp v118, v126, v142 row_shr:1 row_mask:0xf bank_mask:0xf
	v_fmac_f32_dpp v119, v127, v143 row_shr:1 row_mask:0xf bank_mask:0xf
	v_fmac_f32_dpp v112, v120, v144 row_shr:1 row_mask:0xf bank_mask:0xf
	v_fmac_f32_dpp v113, v121, v145 row_shr:1 row_mask:0xf bank_mask:0xf
	v_fmac_f32_dpp v114, v122, v146 row_shr:1 row_mask:0xf bank_mask:0xf
	v_fmac_f32_dpp v115, v123, v147 row_shr:1 row_mask:0xf bank_mask:0xf
	v_fmac_f32_dpp v116, v124, v148 row_shr:2 row_mask:0xf bank_mask:0xf
	v_fmac_f32_dpp v117, v125, v149 row_shr:2 row_mask:0xf bank_mask:0xf
	v_fmac_f32_dpp v118, v126, v150 row_shr:2 row_mask:0xf bank_mask:0xf
	v_fmac_f32_dpp v119, v127, v151 row_shr:2 row_mask:0xf bank_mask:0xf
	v_fmac_f32_dpp v112, v120, v152 row_shr:2 row_mask:0xf bank_mask:0xf
	v_fmac_f32_dpp v113, v121, v153 row_shr:2 row_mask:0xf bank_mask:0xf
	v_fmac_f32_dpp v114, v122, v154 row_shr:2 row_mask:0xf bank_mask:0xf
	v_fmac_f32_dpp v115, v123, v155 row_shr:2 row_mask:0xf bank_mask:0xf
	v_fmac_f32_dpp v116, v8, v140 row_shl:15 row_mask:0xf bank_mask:0xf
	v_fmac_f32_dpp v117, v9, v141 row_shl:15 row_mask:0xf bank_mask:0xf
	v_fmac_f32_dpp v118, v10, v142 row_shl:15 row_mask:0xf bank_mask:0xf
	v_fmac_f32_dpp v119, v11, v143 row_shl:15 row_mask:0xf bank_mask:0xf
	v_fmac_f32_dpp v112, v128, v144 row_shl:15 row_mask:0xf bank_mask:0xf
	v_fmac_f32_dpp v113, v129, v145 row_shl:15 row_mask:0xf bank_mask:0xf
	v_fmac_f32_dpp v114, v130, v146 row_shl:15 row_mask:0xf bank_mask:0xf
	v_fmac_f32_dpp v115, v131, v147 row_shl:15 row_mask:0xf bank_mask:0xf
	v_fmac_f32_dpp v116, v8, v148 row_shl:14 row_mask:0xf bank_mask:0xf
	v_fmac_f32_dpp v117, v9, v149 row_shl:14 row_mask:0xf bank_mask:0xf
	v_fmac_f32_dpp v118, v10, v150 row_shl:14 row_mask:0xf bank_mask:0xf
	v_fmac_f32_dpp v119, v11, v151 row_shl:14 row_mask:0xf bank_mask:0xf
	v_fmac_f32_dpp v112, v128, v152 row_shl:14 row_mask:0xf bank_mask:0xf
	v_fmac_f32_dpp v113, v129, v153 row_shl:14 row_mask:0xf bank_mask:0xf
	v_fmac_f32_dpp v114, v130, v154 row_shl:14 row_mask:0xf bank_mask:0xf
	v_fmac_f32_dpp v115, v131, v155 row_shl:14 row_mask:0xf bank_mask:0xf
	s_waitcnt lgkmcnt(0)
	v_fma_f32 v124, v132, v8, v156
	v_fma_f32 v125, v133, v9, v157
	v_fma_f32 v126, v134, v10, v158
	v_fma_f32 v127, v135, v11, v159
	v_fma_f32 v120, v136, v128, v160
	v_fma_f32 v121, v137, v129, v161
	v_fma_f32 v122, v138, v130, v162
	v_fma_f32 v123, v139, v131, v163
	v_fmac_f32_dpp v124, v8, v140 row_shr:1 row_mask:0xf bank_mask:0xf
	v_fmac_f32_dpp v125, v9, v141 row_shr:1 row_mask:0xf bank_mask:0xf
	v_fmac_f32_dpp v126, v10, v142 row_shr:1 row_mask:0xf bank_mask:0xf
	v_fmac_f32_dpp v127, v11, v143 row_shr:1 row_mask:0xf bank_mask:0xf
	v_fmac_f32_dpp v120, v128, v144 row_shr:1 row_mask:0xf bank_mask:0xf
	v_fmac_f32_dpp v121, v129, v145 row_shr:1 row_mask:0xf bank_mask:0xf
	v_fmac_f32_dpp v122, v130, v146 row_shr:1 row_mask:0xf bank_mask:0xf
	v_fmac_f32_dpp v123, v131, v147 row_shr:1 row_mask:0xf bank_mask:0xf
	v_fmac_f32_dpp v124, v8, v148 row_shr:2 row_mask:0xf bank_mask:0xf
	v_fmac_f32_dpp v125, v9, v149 row_shr:2 row_mask:0xf bank_mask:0xf
	v_fmac_f32_dpp v126, v10, v150 row_shr:2 row_mask:0xf bank_mask:0xf
	v_fmac_f32_dpp v127, v11, v151 row_shr:2 row_mask:0xf bank_mask:0xf
	v_fmac_f32_dpp v120, v128, v152 row_shr:2 row_mask:0xf bank_mask:0xf
	v_fmac_f32_dpp v121, v129, v153 row_shr:2 row_mask:0xf bank_mask:0xf
	v_fmac_f32_dpp v122, v130, v154 row_shr:2 row_mask:0xf bank_mask:0xf
	v_fmac_f32_dpp v123, v131, v155 row_shr:2 row_mask:0xf bank_mask:0xf
	v_fmac_f32_dpp v124, v246, v140 row_shl:15 row_mask:0xf bank_mask:0xf
	v_fmac_f32_dpp v125, v247, v141 row_shl:15 row_mask:0xf bank_mask:0xf
	v_fmac_f32_dpp v126, v248, v142 row_shl:15 row_mask:0xf bank_mask:0xf
	v_fmac_f32_dpp v127, v249, v143 row_shl:15 row_mask:0xf bank_mask:0xf
	v_fmac_f32_dpp v120, v250, v144 row_shl:15 row_mask:0xf bank_mask:0xf
	v_fmac_f32_dpp v121, v251, v145 row_shl:15 row_mask:0xf bank_mask:0xf
	v_fmac_f32_dpp v122, v252, v146 row_shl:15 row_mask:0xf bank_mask:0xf
	v_fmac_f32_dpp v123, v253, v147 row_shl:15 row_mask:0xf bank_mask:0xf
	v_fmac_f32_dpp v124, v246, v148 row_shl:14 row_mask:0xf bank_mask:0xf
	v_fmac_f32_dpp v125, v247, v149 row_shl:14 row_mask:0xf bank_mask:0xf
	v_fmac_f32_dpp v126, v248, v150 row_shl:14 row_mask:0xf bank_mask:0xf
	v_fmac_f32_dpp v127, v249, v151 row_shl:14 row_mask:0xf bank_mask:0xf
	v_fmac_f32_dpp v120, v250, v152 row_shl:14 row_mask:0xf bank_mask:0xf
	v_fmac_f32_dpp v121, v251, v153 row_shl:14 row_mask:0xf bank_mask:0xf
	v_fmac_f32_dpp v122, v252, v154 row_shl:14 row_mask:0xf bank_mask:0xf
	v_fmac_f32_dpp v123, v253, v155 row_shl:14 row_mask:0xf bank_mask:0xf
	s_mov_b32 exec_lo, 0xc000c000
	s_mov_b32 exec_hi, 0xc000c000
	ds_read_b128 v[246:249], v234 offset:512
	ds_read_b128 v[250:253], v234 offset:528
	s_mov_b64 exec, -1
	s_waitcnt vmcnt(4)
	v_fma_f32 v8, v194, v76, v226
	v_fma_f32 v9, v195, v77, v227
	v_fma_f32 v10, v196, v78, v228
	v_fma_f32 v11, v197, v79, v229
	v_fma_f32 v128, v198, v72, v230
	v_fma_f32 v129, v199, v73, v231
	v_fma_f32 v130, v200, v74, v232
	v_fma_f32 v131, v201, v75, v233
	v_fmac_f32_dpp v8, v76, v202 row_shr:1 row_mask:0xf bank_mask:0xf
	v_fmac_f32_dpp v9, v77, v203 row_shr:1 row_mask:0xf bank_mask:0xf
	v_fmac_f32_dpp v10, v78, v204 row_shr:1 row_mask:0xf bank_mask:0xf
	v_fmac_f32_dpp v11, v79, v205 row_shr:1 row_mask:0xf bank_mask:0xf
	v_fmac_f32_dpp v128, v72, v206 row_shr:1 row_mask:0xf bank_mask:0xf
	v_fmac_f32_dpp v129, v73, v207 row_shr:1 row_mask:0xf bank_mask:0xf
	v_fmac_f32_dpp v130, v74, v208 row_shr:1 row_mask:0xf bank_mask:0xf
	v_fmac_f32_dpp v131, v75, v209 row_shr:1 row_mask:0xf bank_mask:0xf
	v_fmac_f32_dpp v8, v76, v210 row_shr:2 row_mask:0xf bank_mask:0xf
	v_fmac_f32_dpp v9, v77, v211 row_shr:2 row_mask:0xf bank_mask:0xf
	v_fmac_f32_dpp v10, v78, v212 row_shr:2 row_mask:0xf bank_mask:0xf
	v_fmac_f32_dpp v11, v79, v213 row_shr:2 row_mask:0xf bank_mask:0xf
	v_fmac_f32_dpp v128, v72, v214 row_shr:2 row_mask:0xf bank_mask:0xf
	v_fmac_f32_dpp v129, v73, v215 row_shr:2 row_mask:0xf bank_mask:0xf
	v_fmac_f32_dpp v130, v74, v216 row_shr:2 row_mask:0xf bank_mask:0xf
	v_fmac_f32_dpp v131, v75, v217 row_shr:2 row_mask:0xf bank_mask:0xf
	v_fmac_f32_dpp v8, v84, v202 row_shl:15 row_mask:0xf bank_mask:0xf
	v_fmac_f32_dpp v9, v85, v203 row_shl:15 row_mask:0xf bank_mask:0xf
	v_fmac_f32_dpp v10, v86, v204 row_shl:15 row_mask:0xf bank_mask:0xf
	v_fmac_f32_dpp v11, v87, v205 row_shl:15 row_mask:0xf bank_mask:0xf
	v_fmac_f32_dpp v128, v80, v206 row_shl:15 row_mask:0xf bank_mask:0xf
	v_fmac_f32_dpp v129, v81, v207 row_shl:15 row_mask:0xf bank_mask:0xf
	v_fmac_f32_dpp v130, v82, v208 row_shl:15 row_mask:0xf bank_mask:0xf
	v_fmac_f32_dpp v131, v83, v209 row_shl:15 row_mask:0xf bank_mask:0xf
	v_fmac_f32_dpp v8, v84, v210 row_shl:14 row_mask:0xf bank_mask:0xf
	v_fmac_f32_dpp v9, v85, v211 row_shl:14 row_mask:0xf bank_mask:0xf
	v_fmac_f32_dpp v10, v86, v212 row_shl:14 row_mask:0xf bank_mask:0xf
	v_fmac_f32_dpp v11, v87, v213 row_shl:14 row_mask:0xf bank_mask:0xf
	v_fmac_f32_dpp v128, v80, v214 row_shl:14 row_mask:0xf bank_mask:0xf
	v_fmac_f32_dpp v129, v81, v215 row_shl:14 row_mask:0xf bank_mask:0xf
	v_fmac_f32_dpp v130, v82, v216 row_shl:14 row_mask:0xf bank_mask:0xf
	v_fmac_f32_dpp v131, v83, v217 row_shl:14 row_mask:0xf bank_mask:0xf
	v_fma_f32 v76, v194, v84, v226
	v_fma_f32 v77, v195, v85, v227
	v_fma_f32 v78, v196, v86, v228
	v_fma_f32 v79, v197, v87, v229
	v_fma_f32 v72, v198, v80, v230
	v_fma_f32 v73, v199, v81, v231
	v_fma_f32 v74, v200, v82, v232
	v_fma_f32 v75, v201, v83, v233
	v_fmac_f32_dpp v76, v84, v202 row_shr:1 row_mask:0xf bank_mask:0xf
	v_fmac_f32_dpp v77, v85, v203 row_shr:1 row_mask:0xf bank_mask:0xf
	v_fmac_f32_dpp v78, v86, v204 row_shr:1 row_mask:0xf bank_mask:0xf
	v_fmac_f32_dpp v79, v87, v205 row_shr:1 row_mask:0xf bank_mask:0xf
	v_fmac_f32_dpp v72, v80, v206 row_shr:1 row_mask:0xf bank_mask:0xf
	v_fmac_f32_dpp v73, v81, v207 row_shr:1 row_mask:0xf bank_mask:0xf
	v_fmac_f32_dpp v74, v82, v208 row_shr:1 row_mask:0xf bank_mask:0xf
	v_fmac_f32_dpp v75, v83, v209 row_shr:1 row_mask:0xf bank_mask:0xf
	v_fmac_f32_dpp v76, v84, v210 row_shr:2 row_mask:0xf bank_mask:0xf
	v_fmac_f32_dpp v77, v85, v211 row_shr:2 row_mask:0xf bank_mask:0xf
	v_fmac_f32_dpp v78, v86, v212 row_shr:2 row_mask:0xf bank_mask:0xf
	v_fmac_f32_dpp v79, v87, v213 row_shr:2 row_mask:0xf bank_mask:0xf
	v_fmac_f32_dpp v72, v80, v214 row_shr:2 row_mask:0xf bank_mask:0xf
	v_fmac_f32_dpp v73, v81, v215 row_shr:2 row_mask:0xf bank_mask:0xf
	v_fmac_f32_dpp v74, v82, v216 row_shr:2 row_mask:0xf bank_mask:0xf
	v_fmac_f32_dpp v75, v83, v217 row_shr:2 row_mask:0xf bank_mask:0xf
	v_fmac_f32_dpp v76, v92, v202 row_shl:15 row_mask:0xf bank_mask:0xf
	v_fmac_f32_dpp v77, v93, v203 row_shl:15 row_mask:0xf bank_mask:0xf
	v_fmac_f32_dpp v78, v94, v204 row_shl:15 row_mask:0xf bank_mask:0xf
	v_fmac_f32_dpp v79, v95, v205 row_shl:15 row_mask:0xf bank_mask:0xf
	v_fmac_f32_dpp v72, v88, v206 row_shl:15 row_mask:0xf bank_mask:0xf
	v_fmac_f32_dpp v73, v89, v207 row_shl:15 row_mask:0xf bank_mask:0xf
	v_fmac_f32_dpp v74, v90, v208 row_shl:15 row_mask:0xf bank_mask:0xf
	v_fmac_f32_dpp v75, v91, v209 row_shl:15 row_mask:0xf bank_mask:0xf
	v_fmac_f32_dpp v76, v92, v210 row_shl:14 row_mask:0xf bank_mask:0xf
	v_fmac_f32_dpp v77, v93, v211 row_shl:14 row_mask:0xf bank_mask:0xf
	v_fmac_f32_dpp v78, v94, v212 row_shl:14 row_mask:0xf bank_mask:0xf
	v_fmac_f32_dpp v79, v95, v213 row_shl:14 row_mask:0xf bank_mask:0xf
	v_fmac_f32_dpp v72, v88, v214 row_shl:14 row_mask:0xf bank_mask:0xf
	v_fmac_f32_dpp v73, v89, v215 row_shl:14 row_mask:0xf bank_mask:0xf
	v_fmac_f32_dpp v74, v90, v216 row_shl:14 row_mask:0xf bank_mask:0xf
	v_fmac_f32_dpp v75, v91, v217 row_shl:14 row_mask:0xf bank_mask:0xf
	v_fma_f32 v84, v194, v92, v226
	v_fma_f32 v85, v195, v93, v227
	v_fma_f32 v86, v196, v94, v228
	v_fma_f32 v87, v197, v95, v229
	v_fma_f32 v80, v198, v88, v230
	v_fma_f32 v81, v199, v89, v231
	v_fma_f32 v82, v200, v90, v232
	v_fma_f32 v83, v201, v91, v233
	v_fmac_f32_dpp v84, v92, v202 row_shr:1 row_mask:0xf bank_mask:0xf
	v_fmac_f32_dpp v85, v93, v203 row_shr:1 row_mask:0xf bank_mask:0xf
	v_fmac_f32_dpp v86, v94, v204 row_shr:1 row_mask:0xf bank_mask:0xf
	v_fmac_f32_dpp v87, v95, v205 row_shr:1 row_mask:0xf bank_mask:0xf
	v_fmac_f32_dpp v80, v88, v206 row_shr:1 row_mask:0xf bank_mask:0xf
	v_fmac_f32_dpp v81, v89, v207 row_shr:1 row_mask:0xf bank_mask:0xf
	v_fmac_f32_dpp v82, v90, v208 row_shr:1 row_mask:0xf bank_mask:0xf
	v_fmac_f32_dpp v83, v91, v209 row_shr:1 row_mask:0xf bank_mask:0xf
	v_fmac_f32_dpp v84, v92, v210 row_shr:2 row_mask:0xf bank_mask:0xf
	v_fmac_f32_dpp v85, v93, v211 row_shr:2 row_mask:0xf bank_mask:0xf
	v_fmac_f32_dpp v86, v94, v212 row_shr:2 row_mask:0xf bank_mask:0xf
	v_fmac_f32_dpp v87, v95, v213 row_shr:2 row_mask:0xf bank_mask:0xf
	v_fmac_f32_dpp v80, v88, v214 row_shr:2 row_mask:0xf bank_mask:0xf
	v_fmac_f32_dpp v81, v89, v215 row_shr:2 row_mask:0xf bank_mask:0xf
	v_fmac_f32_dpp v82, v90, v216 row_shr:2 row_mask:0xf bank_mask:0xf
	v_fmac_f32_dpp v83, v91, v217 row_shr:2 row_mask:0xf bank_mask:0xf
	v_fmac_f32_dpp v84, v100, v202 row_shl:15 row_mask:0xf bank_mask:0xf
	v_fmac_f32_dpp v85, v101, v203 row_shl:15 row_mask:0xf bank_mask:0xf
	v_fmac_f32_dpp v86, v102, v204 row_shl:15 row_mask:0xf bank_mask:0xf
	v_fmac_f32_dpp v87, v103, v205 row_shl:15 row_mask:0xf bank_mask:0xf
	v_fmac_f32_dpp v80, v96, v206 row_shl:15 row_mask:0xf bank_mask:0xf
	v_fmac_f32_dpp v81, v97, v207 row_shl:15 row_mask:0xf bank_mask:0xf
	v_fmac_f32_dpp v82, v98, v208 row_shl:15 row_mask:0xf bank_mask:0xf
	v_fmac_f32_dpp v83, v99, v209 row_shl:15 row_mask:0xf bank_mask:0xf
	v_fmac_f32_dpp v84, v100, v210 row_shl:14 row_mask:0xf bank_mask:0xf
	v_fmac_f32_dpp v85, v101, v211 row_shl:14 row_mask:0xf bank_mask:0xf
	v_fmac_f32_dpp v86, v102, v212 row_shl:14 row_mask:0xf bank_mask:0xf
	v_fmac_f32_dpp v87, v103, v213 row_shl:14 row_mask:0xf bank_mask:0xf
	v_fmac_f32_dpp v80, v96, v214 row_shl:14 row_mask:0xf bank_mask:0xf
	v_fmac_f32_dpp v81, v97, v215 row_shl:14 row_mask:0xf bank_mask:0xf
	v_fmac_f32_dpp v82, v98, v216 row_shl:14 row_mask:0xf bank_mask:0xf
	v_fmac_f32_dpp v83, v99, v217 row_shl:14 row_mask:0xf bank_mask:0xf
	s_waitcnt lgkmcnt(0)
	v_fma_f32 v92, v194, v100, v226
	v_fma_f32 v93, v195, v101, v227
	v_fma_f32 v94, v196, v102, v228
	v_fma_f32 v95, v197, v103, v229
	v_fma_f32 v88, v198, v96, v230
	v_fma_f32 v89, v199, v97, v231
	v_fma_f32 v90, v200, v98, v232
	v_fma_f32 v91, v201, v99, v233
	v_fmac_f32_dpp v92, v100, v202 row_shr:1 row_mask:0xf bank_mask:0xf
	v_fmac_f32_dpp v93, v101, v203 row_shr:1 row_mask:0xf bank_mask:0xf
	v_fmac_f32_dpp v94, v102, v204 row_shr:1 row_mask:0xf bank_mask:0xf
	v_fmac_f32_dpp v95, v103, v205 row_shr:1 row_mask:0xf bank_mask:0xf
	v_fmac_f32_dpp v88, v96, v206 row_shr:1 row_mask:0xf bank_mask:0xf
	v_fmac_f32_dpp v89, v97, v207 row_shr:1 row_mask:0xf bank_mask:0xf
	v_fmac_f32_dpp v90, v98, v208 row_shr:1 row_mask:0xf bank_mask:0xf
	v_fmac_f32_dpp v91, v99, v209 row_shr:1 row_mask:0xf bank_mask:0xf
	v_fmac_f32_dpp v92, v100, v210 row_shr:2 row_mask:0xf bank_mask:0xf
	v_fmac_f32_dpp v93, v101, v211 row_shr:2 row_mask:0xf bank_mask:0xf
	v_fmac_f32_dpp v94, v102, v212 row_shr:2 row_mask:0xf bank_mask:0xf
	v_fmac_f32_dpp v95, v103, v213 row_shr:2 row_mask:0xf bank_mask:0xf
	v_fmac_f32_dpp v88, v96, v214 row_shr:2 row_mask:0xf bank_mask:0xf
	v_fmac_f32_dpp v89, v97, v215 row_shr:2 row_mask:0xf bank_mask:0xf
	v_fmac_f32_dpp v90, v98, v216 row_shr:2 row_mask:0xf bank_mask:0xf
	v_fmac_f32_dpp v91, v99, v217 row_shr:2 row_mask:0xf bank_mask:0xf
	v_fmac_f32_dpp v92, v246, v202 row_shl:15 row_mask:0xf bank_mask:0xf
	v_fmac_f32_dpp v93, v247, v203 row_shl:15 row_mask:0xf bank_mask:0xf
	v_fmac_f32_dpp v94, v248, v204 row_shl:15 row_mask:0xf bank_mask:0xf
	v_fmac_f32_dpp v95, v249, v205 row_shl:15 row_mask:0xf bank_mask:0xf
	v_fmac_f32_dpp v88, v250, v206 row_shl:15 row_mask:0xf bank_mask:0xf
	v_fmac_f32_dpp v89, v251, v207 row_shl:15 row_mask:0xf bank_mask:0xf
	v_fmac_f32_dpp v90, v252, v208 row_shl:15 row_mask:0xf bank_mask:0xf
	v_fmac_f32_dpp v91, v253, v209 row_shl:15 row_mask:0xf bank_mask:0xf
	v_fmac_f32_dpp v92, v246, v210 row_shl:14 row_mask:0xf bank_mask:0xf
	v_fmac_f32_dpp v93, v247, v211 row_shl:14 row_mask:0xf bank_mask:0xf
	v_fmac_f32_dpp v94, v248, v212 row_shl:14 row_mask:0xf bank_mask:0xf
	v_fmac_f32_dpp v95, v249, v213 row_shl:14 row_mask:0xf bank_mask:0xf
	v_fmac_f32_dpp v88, v250, v214 row_shl:14 row_mask:0xf bank_mask:0xf
	v_fmac_f32_dpp v89, v251, v215 row_shl:14 row_mask:0xf bank_mask:0xf
	v_fmac_f32_dpp v90, v252, v216 row_shl:14 row_mask:0xf bank_mask:0xf
	v_fmac_f32_dpp v91, v253, v217 row_shl:14 row_mask:0xf bank_mask:0xf
	v_mul_f32_e32 v246, 0xbfb8aa3b, v176
	v_mul_f32_e32 v247, 0xbfb8aa3b, v177
	v_mul_f32_e32 v248, 0xbfb8aa3b, v178
	v_mul_f32_e32 v249, 0xbfb8aa3b, v179
	v_mul_f32_e32 v250, 0xbfb8aa3b, v182
	v_mul_f32_e32 v251, 0xbfb8aa3b, v183
	v_mul_f32_e32 v252, 0xbfb8aa3b, v184
	v_mul_f32_e32 v253, 0xbfb8aa3b, v185
	v_exp_f32_e32 v246, v246
	v_exp_f32_e32 v247, v247
	v_exp_f32_e32 v248, v248
	v_exp_f32_e32 v249, v249
	v_exp_f32_e32 v250, v250
	v_exp_f32_e32 v251, v251
	v_exp_f32_e32 v252, v252
	v_exp_f32_e32 v253, v253
	v_add_f32_e32 v246, 1.0, v246
	v_add_f32_e32 v247, 1.0, v247
	v_add_f32_e32 v248, 1.0, v248
	v_add_f32_e32 v249, 1.0, v249
	v_add_f32_e32 v250, 1.0, v250
	v_add_f32_e32 v251, 1.0, v251
	v_add_f32_e32 v252, 1.0, v252
	v_add_f32_e32 v253, 1.0, v253
	v_rcp_f32_e32 v246, v246
	v_rcp_f32_e32 v247, v247
	v_rcp_f32_e32 v248, v248
	v_rcp_f32_e32 v249, v249
	v_rcp_f32_e32 v250, v250
	v_rcp_f32_e32 v251, v251
	v_rcp_f32_e32 v252, v252
	v_rcp_f32_e32 v253, v253
	v_mul_f32_e32 v176, v176, v246
	v_mul_f32_e32 v177, v177, v247
	v_mul_f32_e32 v178, v178, v248
	v_mul_f32_e32 v179, v179, v249
	v_mul_f32_e32 v182, v182, v250
	v_mul_f32_e32 v183, v183, v251
	v_mul_f32_e32 v184, v184, v252
	v_mul_f32_e32 v185, v185, v253
	v_mul_f32_e32 v176, v176, v8
	v_mul_f32_e32 v177, v177, v9
	v_mul_f32_e32 v178, v178, v10
	v_mul_f32_e32 v179, v179, v11
	v_mul_f32_e32 v182, v182, v128
	v_mul_f32_e32 v183, v183, v129
	v_mul_f32_e32 v184, v184, v130
	v_mul_f32_e32 v185, v185, v131
	v_cvt_pk_bf16_f32 v176, v176, v177
	v_cvt_pk_bf16_f32 v177, v178, v179
	v_cvt_pk_bf16_f32 v178, v182, v183
	v_cvt_pk_bf16_f32 v179, v184, v185
	v_add_u32_e32 v221, 0x84000, v245
	global_store_dwordx4 v221, v[176:179], s[12:13]
	v_mul_f32_e32 v246, 0xbfb8aa3b, v108
	v_mul_f32_e32 v247, 0xbfb8aa3b, v109
	v_mul_f32_e32 v248, 0xbfb8aa3b, v110
	v_mul_f32_e32 v249, 0xbfb8aa3b, v111
	v_mul_f32_e32 v250, 0xbfb8aa3b, v104
	v_mul_f32_e32 v251, 0xbfb8aa3b, v105
	v_mul_f32_e32 v252, 0xbfb8aa3b, v106
	v_mul_f32_e32 v253, 0xbfb8aa3b, v107
	v_exp_f32_e32 v246, v246
	v_exp_f32_e32 v247, v247
	v_exp_f32_e32 v248, v248
	v_exp_f32_e32 v249, v249
	v_exp_f32_e32 v250, v250
	v_exp_f32_e32 v251, v251
	v_exp_f32_e32 v252, v252
	v_exp_f32_e32 v253, v253
	v_add_f32_e32 v246, 1.0, v246
	v_add_f32_e32 v247, 1.0, v247
	v_add_f32_e32 v248, 1.0, v248
	v_add_f32_e32 v249, 1.0, v249
	v_add_f32_e32 v250, 1.0, v250
	v_add_f32_e32 v251, 1.0, v251
	v_add_f32_e32 v252, 1.0, v252
	v_add_f32_e32 v253, 1.0, v253
	v_rcp_f32_e32 v246, v246
	v_rcp_f32_e32 v247, v247
	v_rcp_f32_e32 v248, v248
	v_rcp_f32_e32 v249, v249
	v_rcp_f32_e32 v250, v250
	v_rcp_f32_e32 v251, v251
	v_rcp_f32_e32 v252, v252
	v_rcp_f32_e32 v253, v253
	v_mul_f32_e32 v108, v108, v246
	v_mul_f32_e32 v109, v109, v247
	v_mul_f32_e32 v110, v110, v248
	v_mul_f32_e32 v111, v111, v249
	v_mul_f32_e32 v104, v104, v250
	v_mul_f32_e32 v105, v105, v251
	v_mul_f32_e32 v106, v106, v252
	v_mul_f32_e32 v107, v107, v253
	v_mul_f32_e32 v108, v108, v76
	v_mul_f32_e32 v109, v109, v77
	v_mul_f32_e32 v110, v110, v78
	v_mul_f32_e32 v111, v111, v79
	v_mul_f32_e32 v104, v104, v72
	v_mul_f32_e32 v105, v105, v73
	v_mul_f32_e32 v106, v106, v74
	v_mul_f32_e32 v107, v107, v75
	v_cvt_pk_bf16_f32 v108, v108, v109
	v_cvt_pk_bf16_f32 v109, v110, v111
	v_cvt_pk_bf16_f32 v110, v104, v105
	v_cvt_pk_bf16_f32 v111, v106, v107
	v_add_u32_e32 v240, 0x58000, v245
	global_store_dwordx4 v240, v[108:111], s[12:13]
	v_mul_f32_e32 v246, 0xbfb8aa3b, v116
	v_mul_f32_e32 v247, 0xbfb8aa3b, v117
	v_mul_f32_e32 v248, 0xbfb8aa3b, v118
	v_mul_f32_e32 v249, 0xbfb8aa3b, v119
	v_mul_f32_e32 v250, 0xbfb8aa3b, v112
	v_mul_f32_e32 v251, 0xbfb8aa3b, v113
	v_mul_f32_e32 v252, 0xbfb8aa3b, v114
	v_mul_f32_e32 v253, 0xbfb8aa3b, v115
	v_exp_f32_e32 v246, v246
	v_exp_f32_e32 v247, v247
	v_exp_f32_e32 v248, v248
	v_exp_f32_e32 v249, v249
	v_exp_f32_e32 v250, v250
	v_exp_f32_e32 v251, v251
	v_exp_f32_e32 v252, v252
	v_exp_f32_e32 v253, v253
	v_add_f32_e32 v246, 1.0, v246
	v_add_f32_e32 v247, 1.0, v247
	v_add_f32_e32 v248, 1.0, v248
	v_add_f32_e32 v249, 1.0, v249
	v_add_f32_e32 v250, 1.0, v250
	v_add_f32_e32 v251, 1.0, v251
	v_add_f32_e32 v252, 1.0, v252
	v_add_f32_e32 v253, 1.0, v253
	v_rcp_f32_e32 v246, v246
	v_rcp_f32_e32 v247, v247
	v_rcp_f32_e32 v248, v248
	v_rcp_f32_e32 v249, v249
	v_rcp_f32_e32 v250, v250
	v_rcp_f32_e32 v251, v251
	v_rcp_f32_e32 v252, v252
	v_rcp_f32_e32 v253, v253
	v_mul_f32_e32 v116, v116, v246
	v_mul_f32_e32 v117, v117, v247
	v_mul_f32_e32 v118, v118, v248
	v_mul_f32_e32 v119, v119, v249
	v_mul_f32_e32 v112, v112, v250
	v_mul_f32_e32 v113, v113, v251
	v_mul_f32_e32 v114, v114, v252
	v_mul_f32_e32 v115, v115, v253
	v_mul_f32_e32 v116, v116, v84
	v_mul_f32_e32 v117, v117, v85
	v_mul_f32_e32 v118, v118, v86
	v_mul_f32_e32 v119, v119, v87
	v_mul_f32_e32 v112, v112, v80
	v_mul_f32_e32 v113, v113, v81
	v_mul_f32_e32 v114, v114, v82
	v_mul_f32_e32 v115, v115, v83
	v_cvt_pk_bf16_f32 v116, v116, v117
	v_cvt_pk_bf16_f32 v117, v118, v119
	v_cvt_pk_bf16_f32 v118, v112, v113
	v_cvt_pk_bf16_f32 v119, v114, v115
	v_add_u32_e32 v221, 0x2c000, v245
	global_store_dwordx4 v221, v[116:119], s[12:13]
	v_mul_f32_e32 v246, 0xbfb8aa3b, v124
	v_mul_f32_e32 v247, 0xbfb8aa3b, v125
	v_mul_f32_e32 v248, 0xbfb8aa3b, v126
	v_mul_f32_e32 v249, 0xbfb8aa3b, v127
	v_mul_f32_e32 v250, 0xbfb8aa3b, v120
	v_mul_f32_e32 v251, 0xbfb8aa3b, v121
	v_mul_f32_e32 v252, 0xbfb8aa3b, v122
	v_mul_f32_e32 v253, 0xbfb8aa3b, v123
	v_exp_f32_e32 v246, v246
	v_exp_f32_e32 v247, v247
	v_exp_f32_e32 v248, v248
	v_exp_f32_e32 v249, v249
	v_exp_f32_e32 v250, v250
	v_exp_f32_e32 v251, v251
	v_exp_f32_e32 v252, v252
	v_exp_f32_e32 v253, v253
	v_add_f32_e32 v246, 1.0, v246
	v_add_f32_e32 v247, 1.0, v247
	v_add_f32_e32 v248, 1.0, v248
	v_add_f32_e32 v249, 1.0, v249
	v_add_f32_e32 v250, 1.0, v250
	v_add_f32_e32 v251, 1.0, v251
	v_add_f32_e32 v252, 1.0, v252
	v_add_f32_e32 v253, 1.0, v253
	v_rcp_f32_e32 v246, v246
	v_rcp_f32_e32 v247, v247
	v_rcp_f32_e32 v248, v248
	v_rcp_f32_e32 v249, v249
	v_rcp_f32_e32 v250, v250
	v_rcp_f32_e32 v251, v251
	v_rcp_f32_e32 v252, v252
	v_rcp_f32_e32 v253, v253
	v_mul_f32_e32 v124, v124, v246
	v_mul_f32_e32 v125, v125, v247
	v_mul_f32_e32 v126, v126, v248
	v_mul_f32_e32 v127, v127, v249
	v_mul_f32_e32 v120, v120, v250
	v_mul_f32_e32 v121, v121, v251
	v_mul_f32_e32 v122, v122, v252
	v_mul_f32_e32 v123, v123, v253
	v_mul_f32_e32 v124, v124, v92
	v_mul_f32_e32 v125, v125, v93
	v_mul_f32_e32 v126, v126, v94
	v_mul_f32_e32 v127, v127, v95
	v_mul_f32_e32 v120, v120, v88
	v_mul_f32_e32 v121, v121, v89
	v_mul_f32_e32 v122, v122, v90
	v_mul_f32_e32 v123, v123, v91
	v_cvt_pk_bf16_f32 v124, v124, v125
	v_cvt_pk_bf16_f32 v125, v126, v127
	v_cvt_pk_bf16_f32 v126, v120, v121
	v_cvt_pk_bf16_f32 v127, v122, v123
	global_store_dwordx4 v245, v[124:127], s[12:13]
	s_mov_b32 exec_lo, 0xc000c000
	s_mov_b32 exec_hi, 0xc000c000
	ds_read_b128 v[246:249], v234 offset:4096
	ds_read_b128 v[250:253], v234 offset:4112
	s_mov_b64 exec, -1
	v_fma_f32 v176, v132, v44, v156
	v_fma_f32 v177, v133, v45, v157
	v_fma_f32 v178, v134, v46, v158
	v_fma_f32 v179, v135, v47, v159
	v_fma_f32 v182, v136, v40, v160
	v_fma_f32 v183, v137, v41, v161
	v_fma_f32 v184, v138, v42, v162
	v_fma_f32 v185, v139, v43, v163
	v_fmac_f32_dpp v176, v44, v140 row_shr:1 row_mask:0xf bank_mask:0xf
	v_fmac_f32_dpp v177, v45, v141 row_shr:1 row_mask:0xf bank_mask:0xf
	v_fmac_f32_dpp v178, v46, v142 row_shr:1 row_mask:0xf bank_mask:0xf
	v_fmac_f32_dpp v179, v47, v143 row_shr:1 row_mask:0xf bank_mask:0xf
	v_fmac_f32_dpp v182, v40, v144 row_shr:1 row_mask:0xf bank_mask:0xf
	v_fmac_f32_dpp v183, v41, v145 row_shr:1 row_mask:0xf bank_mask:0xf
	v_fmac_f32_dpp v184, v42, v146 row_shr:1 row_mask:0xf bank_mask:0xf
	v_fmac_f32_dpp v185, v43, v147 row_shr:1 row_mask:0xf bank_mask:0xf
	v_fmac_f32_dpp v176, v44, v148 row_shr:2 row_mask:0xf bank_mask:0xf
	v_fmac_f32_dpp v177, v45, v149 row_shr:2 row_mask:0xf bank_mask:0xf
	v_fmac_f32_dpp v178, v46, v150 row_shr:2 row_mask:0xf bank_mask:0xf
	v_fmac_f32_dpp v179, v47, v151 row_shr:2 row_mask:0xf bank_mask:0xf
	v_fmac_f32_dpp v182, v40, v152 row_shr:2 row_mask:0xf bank_mask:0xf
	v_fmac_f32_dpp v183, v41, v153 row_shr:2 row_mask:0xf bank_mask:0xf
	v_fmac_f32_dpp v184, v42, v154 row_shr:2 row_mask:0xf bank_mask:0xf
	v_fmac_f32_dpp v185, v43, v155 row_shr:2 row_mask:0xf bank_mask:0xf
	v_fmac_f32_dpp v176, v52, v140 row_shl:15 row_mask:0xf bank_mask:0xf
	v_fmac_f32_dpp v177, v53, v141 row_shl:15 row_mask:0xf bank_mask:0xf
	v_fmac_f32_dpp v178, v54, v142 row_shl:15 row_mask:0xf bank_mask:0xf
	v_fmac_f32_dpp v179, v55, v143 row_shl:15 row_mask:0xf bank_mask:0xf
	v_fmac_f32_dpp v182, v48, v144 row_shl:15 row_mask:0xf bank_mask:0xf
	v_fmac_f32_dpp v183, v49, v145 row_shl:15 row_mask:0xf bank_mask:0xf
	v_fmac_f32_dpp v184, v50, v146 row_shl:15 row_mask:0xf bank_mask:0xf
	v_fmac_f32_dpp v185, v51, v147 row_shl:15 row_mask:0xf bank_mask:0xf
	v_fmac_f32_dpp v176, v52, v148 row_shl:14 row_mask:0xf bank_mask:0xf
	v_fmac_f32_dpp v177, v53, v149 row_shl:14 row_mask:0xf bank_mask:0xf
	v_fmac_f32_dpp v178, v54, v150 row_shl:14 row_mask:0xf bank_mask:0xf
	v_fmac_f32_dpp v179, v55, v151 row_shl:14 row_mask:0xf bank_mask:0xf
	v_fmac_f32_dpp v182, v48, v152 row_shl:14 row_mask:0xf bank_mask:0xf
	v_fmac_f32_dpp v183, v49, v153 row_shl:14 row_mask:0xf bank_mask:0xf
	v_fmac_f32_dpp v184, v50, v154 row_shl:14 row_mask:0xf bank_mask:0xf
	v_fmac_f32_dpp v185, v51, v155 row_shl:14 row_mask:0xf bank_mask:0xf
	v_fma_f32 v44, v132, v52, v156
	v_fma_f32 v45, v133, v53, v157
	v_fma_f32 v46, v134, v54, v158
	v_fma_f32 v47, v135, v55, v159
	v_fma_f32 v40, v136, v48, v160
	v_fma_f32 v41, v137, v49, v161
	v_fma_f32 v42, v138, v50, v162
	v_fma_f32 v43, v139, v51, v163
	v_fmac_f32_dpp v44, v52, v140 row_shr:1 row_mask:0xf bank_mask:0xf
	v_fmac_f32_dpp v45, v53, v141 row_shr:1 row_mask:0xf bank_mask:0xf
	v_fmac_f32_dpp v46, v54, v142 row_shr:1 row_mask:0xf bank_mask:0xf
	v_fmac_f32_dpp v47, v55, v143 row_shr:1 row_mask:0xf bank_mask:0xf
	v_fmac_f32_dpp v40, v48, v144 row_shr:1 row_mask:0xf bank_mask:0xf
	v_fmac_f32_dpp v41, v49, v145 row_shr:1 row_mask:0xf bank_mask:0xf
	v_fmac_f32_dpp v42, v50, v146 row_shr:1 row_mask:0xf bank_mask:0xf
	v_fmac_f32_dpp v43, v51, v147 row_shr:1 row_mask:0xf bank_mask:0xf
	v_fmac_f32_dpp v44, v52, v148 row_shr:2 row_mask:0xf bank_mask:0xf
	v_fmac_f32_dpp v45, v53, v149 row_shr:2 row_mask:0xf bank_mask:0xf
	v_fmac_f32_dpp v46, v54, v150 row_shr:2 row_mask:0xf bank_mask:0xf
	v_fmac_f32_dpp v47, v55, v151 row_shr:2 row_mask:0xf bank_mask:0xf
	v_fmac_f32_dpp v40, v48, v152 row_shr:2 row_mask:0xf bank_mask:0xf
	v_fmac_f32_dpp v41, v49, v153 row_shr:2 row_mask:0xf bank_mask:0xf
	v_fmac_f32_dpp v42, v50, v154 row_shr:2 row_mask:0xf bank_mask:0xf
	v_fmac_f32_dpp v43, v51, v155 row_shr:2 row_mask:0xf bank_mask:0xf
	v_fmac_f32_dpp v44, v60, v140 row_shl:15 row_mask:0xf bank_mask:0xf
	v_fmac_f32_dpp v45, v61, v141 row_shl:15 row_mask:0xf bank_mask:0xf
	v_fmac_f32_dpp v46, v62, v142 row_shl:15 row_mask:0xf bank_mask:0xf
	v_fmac_f32_dpp v47, v63, v143 row_shl:15 row_mask:0xf bank_mask:0xf
	v_fmac_f32_dpp v40, v56, v144 row_shl:15 row_mask:0xf bank_mask:0xf
	v_fmac_f32_dpp v41, v57, v145 row_shl:15 row_mask:0xf bank_mask:0xf
	v_fmac_f32_dpp v42, v58, v146 row_shl:15 row_mask:0xf bank_mask:0xf
	v_fmac_f32_dpp v43, v59, v147 row_shl:15 row_mask:0xf bank_mask:0xf
	v_fmac_f32_dpp v44, v60, v148 row_shl:14 row_mask:0xf bank_mask:0xf
	v_fmac_f32_dpp v45, v61, v149 row_shl:14 row_mask:0xf bank_mask:0xf
	v_fmac_f32_dpp v46, v62, v150 row_shl:14 row_mask:0xf bank_mask:0xf
	v_fmac_f32_dpp v47, v63, v151 row_shl:14 row_mask:0xf bank_mask:0xf
	v_fmac_f32_dpp v40, v56, v152 row_shl:14 row_mask:0xf bank_mask:0xf
	v_fmac_f32_dpp v41, v57, v153 row_shl:14 row_mask:0xf bank_mask:0xf
	v_fmac_f32_dpp v42, v58, v154 row_shl:14 row_mask:0xf bank_mask:0xf
	v_fmac_f32_dpp v43, v59, v155 row_shl:14 row_mask:0xf bank_mask:0xf
	v_fma_f32 v52, v132, v60, v156
	v_fma_f32 v53, v133, v61, v157
	v_fma_f32 v54, v134, v62, v158
	v_fma_f32 v55, v135, v63, v159
	v_fma_f32 v48, v136, v56, v160
	v_fma_f32 v49, v137, v57, v161
	v_fma_f32 v50, v138, v58, v162
	v_fma_f32 v51, v139, v59, v163
	v_fmac_f32_dpp v52, v60, v140 row_shr:1 row_mask:0xf bank_mask:0xf
	v_fmac_f32_dpp v53, v61, v141 row_shr:1 row_mask:0xf bank_mask:0xf
	v_fmac_f32_dpp v54, v62, v142 row_shr:1 row_mask:0xf bank_mask:0xf
	v_fmac_f32_dpp v55, v63, v143 row_shr:1 row_mask:0xf bank_mask:0xf
	v_fmac_f32_dpp v48, v56, v144 row_shr:1 row_mask:0xf bank_mask:0xf
	v_fmac_f32_dpp v49, v57, v145 row_shr:1 row_mask:0xf bank_mask:0xf
	v_fmac_f32_dpp v50, v58, v146 row_shr:1 row_mask:0xf bank_mask:0xf
	v_fmac_f32_dpp v51, v59, v147 row_shr:1 row_mask:0xf bank_mask:0xf
	v_fmac_f32_dpp v52, v60, v148 row_shr:2 row_mask:0xf bank_mask:0xf
	v_fmac_f32_dpp v53, v61, v149 row_shr:2 row_mask:0xf bank_mask:0xf
	v_fmac_f32_dpp v54, v62, v150 row_shr:2 row_mask:0xf bank_mask:0xf
	v_fmac_f32_dpp v55, v63, v151 row_shr:2 row_mask:0xf bank_mask:0xf
	v_fmac_f32_dpp v48, v56, v152 row_shr:2 row_mask:0xf bank_mask:0xf
	v_fmac_f32_dpp v49, v57, v153 row_shr:2 row_mask:0xf bank_mask:0xf
	v_fmac_f32_dpp v50, v58, v154 row_shr:2 row_mask:0xf bank_mask:0xf
	v_fmac_f32_dpp v51, v59, v155 row_shr:2 row_mask:0xf bank_mask:0xf
	v_fmac_f32_dpp v52, v68, v140 row_shl:15 row_mask:0xf bank_mask:0xf
	v_fmac_f32_dpp v53, v69, v141 row_shl:15 row_mask:0xf bank_mask:0xf
	v_fmac_f32_dpp v54, v70, v142 row_shl:15 row_mask:0xf bank_mask:0xf
	v_fmac_f32_dpp v55, v71, v143 row_shl:15 row_mask:0xf bank_mask:0xf
	v_fmac_f32_dpp v48, v64, v144 row_shl:15 row_mask:0xf bank_mask:0xf
	v_fmac_f32_dpp v49, v65, v145 row_shl:15 row_mask:0xf bank_mask:0xf
	v_fmac_f32_dpp v50, v66, v146 row_shl:15 row_mask:0xf bank_mask:0xf
	v_fmac_f32_dpp v51, v67, v147 row_shl:15 row_mask:0xf bank_mask:0xf
	v_fmac_f32_dpp v52, v68, v148 row_shl:14 row_mask:0xf bank_mask:0xf
	v_fmac_f32_dpp v53, v69, v149 row_shl:14 row_mask:0xf bank_mask:0xf
	v_fmac_f32_dpp v54, v70, v150 row_shl:14 row_mask:0xf bank_mask:0xf
	v_fmac_f32_dpp v55, v71, v151 row_shl:14 row_mask:0xf bank_mask:0xf
	v_fmac_f32_dpp v48, v64, v152 row_shl:14 row_mask:0xf bank_mask:0xf
	v_fmac_f32_dpp v49, v65, v153 row_shl:14 row_mask:0xf bank_mask:0xf
	v_fmac_f32_dpp v50, v66, v154 row_shl:14 row_mask:0xf bank_mask:0xf
	v_fmac_f32_dpp v51, v67, v155 row_shl:14 row_mask:0xf bank_mask:0xf
	s_waitcnt lgkmcnt(0)
	v_fma_f32 v60, v132, v68, v156
	v_fma_f32 v61, v133, v69, v157
	v_fma_f32 v62, v134, v70, v158
	v_fma_f32 v63, v135, v71, v159
	v_fma_f32 v56, v136, v64, v160
	v_fma_f32 v57, v137, v65, v161
	v_fma_f32 v58, v138, v66, v162
	v_fma_f32 v59, v139, v67, v163
	v_fmac_f32_dpp v60, v68, v140 row_shr:1 row_mask:0xf bank_mask:0xf
	v_fmac_f32_dpp v61, v69, v141 row_shr:1 row_mask:0xf bank_mask:0xf
	v_fmac_f32_dpp v62, v70, v142 row_shr:1 row_mask:0xf bank_mask:0xf
	v_fmac_f32_dpp v63, v71, v143 row_shr:1 row_mask:0xf bank_mask:0xf
	v_fmac_f32_dpp v56, v64, v144 row_shr:1 row_mask:0xf bank_mask:0xf
	v_fmac_f32_dpp v57, v65, v145 row_shr:1 row_mask:0xf bank_mask:0xf
	v_fmac_f32_dpp v58, v66, v146 row_shr:1 row_mask:0xf bank_mask:0xf
	v_fmac_f32_dpp v59, v67, v147 row_shr:1 row_mask:0xf bank_mask:0xf
	v_fmac_f32_dpp v60, v68, v148 row_shr:2 row_mask:0xf bank_mask:0xf
	v_fmac_f32_dpp v61, v69, v149 row_shr:2 row_mask:0xf bank_mask:0xf
	v_fmac_f32_dpp v62, v70, v150 row_shr:2 row_mask:0xf bank_mask:0xf
	v_fmac_f32_dpp v63, v71, v151 row_shr:2 row_mask:0xf bank_mask:0xf
	v_fmac_f32_dpp v56, v64, v152 row_shr:2 row_mask:0xf bank_mask:0xf
	v_fmac_f32_dpp v57, v65, v153 row_shr:2 row_mask:0xf bank_mask:0xf
	v_fmac_f32_dpp v58, v66, v154 row_shr:2 row_mask:0xf bank_mask:0xf
	v_fmac_f32_dpp v59, v67, v155 row_shr:2 row_mask:0xf bank_mask:0xf
	v_fmac_f32_dpp v60, v246, v140 row_shl:15 row_mask:0xf bank_mask:0xf
	v_fmac_f32_dpp v61, v247, v141 row_shl:15 row_mask:0xf bank_mask:0xf
	v_fmac_f32_dpp v62, v248, v142 row_shl:15 row_mask:0xf bank_mask:0xf
	v_fmac_f32_dpp v63, v249, v143 row_shl:15 row_mask:0xf bank_mask:0xf
	v_fmac_f32_dpp v56, v250, v144 row_shl:15 row_mask:0xf bank_mask:0xf
	v_fmac_f32_dpp v57, v251, v145 row_shl:15 row_mask:0xf bank_mask:0xf
	v_fmac_f32_dpp v58, v252, v146 row_shl:15 row_mask:0xf bank_mask:0xf
	v_fmac_f32_dpp v59, v253, v147 row_shl:15 row_mask:0xf bank_mask:0xf
	v_fmac_f32_dpp v60, v246, v148 row_shl:14 row_mask:0xf bank_mask:0xf
	v_fmac_f32_dpp v61, v247, v149 row_shl:14 row_mask:0xf bank_mask:0xf
	v_fmac_f32_dpp v62, v248, v150 row_shl:14 row_mask:0xf bank_mask:0xf
	v_fmac_f32_dpp v63, v249, v151 row_shl:14 row_mask:0xf bank_mask:0xf
	v_fmac_f32_dpp v56, v250, v152 row_shl:14 row_mask:0xf bank_mask:0xf
	v_fmac_f32_dpp v57, v251, v153 row_shl:14 row_mask:0xf bank_mask:0xf
	v_fmac_f32_dpp v58, v252, v154 row_shl:14 row_mask:0xf bank_mask:0xf
	v_fmac_f32_dpp v59, v253, v155 row_shl:14 row_mask:0xf bank_mask:0xf
	s_lshl_b32 s37, s24, 8
	v_cndmask_b32_e64 v132, 0, 1, s[10:11]
	s_or_b32 s36, s37, 16
	s_or_b32 s25, s37, 32
	s_or_b32 s23, s37, 48
	v_mov_b32_e32 v156, 0
	v_cmp_ne_u32_e64 s[12:13], 1, v132
	s_andn2_b64 vcc, exec, s[10:11]
	v_mov_b32_e32 v157, 0
	v_mov_b32_e32 v158, 0
	v_mov_b32_e32 v159, 0
	v_mov_b32_e32 v160, 0
	v_mov_b32_e32 v161, 0
	v_mov_b32_e32 v162, 0
	v_mov_b32_e32 v163, 0
	v_mov_b32_e32 v148, 0
	v_mov_b32_e32 v149, 0
	v_mov_b32_e32 v150, 0
	v_mov_b32_e32 v151, 0
	v_mov_b32_e32 v152, 0
	v_mov_b32_e32 v153, 0
	v_mov_b32_e32 v154, 0
	v_mov_b32_e32 v155, 0
	v_mov_b32_e32 v140, 0
	v_mov_b32_e32 v141, 0
	v_mov_b32_e32 v142, 0
	v_mov_b32_e32 v143, 0
	v_mov_b32_e32 v144, 0
	v_mov_b32_e32 v145, 0
	v_mov_b32_e32 v146, 0
	v_mov_b32_e32 v147, 0
	v_mov_b32_e32 v132, 0
	v_mov_b32_e32 v133, 0
	v_mov_b32_e32 v134, 0
	v_mov_b32_e32 v135, 0
	v_mov_b32_e32 v136, 0
	v_mov_b32_e32 v137, 0
	v_mov_b32_e32 v138, 0
	v_mov_b32_e32 v139, 0
	s_cbranch_vccnz .LBB0_1072
	s_cmp_eq_u32 s24, s66
	s_cbranch_scc1 .LBB0_1072
	v_add_u32_e32 v132, s37, v3
	v_ashrrev_i32_e32 v133, 31, v132
	v_lshlrev_b64 v[132:133], 7, v[132:133]
	v_lshl_add_u64 v[132:133], v[170:171], 0, v[132:133]
	global_load_dwordx4 v[156:159], v[132:133], off
	global_load_dwordx4 v[160:163], v[132:133], off offset:16
	v_add_u32_e32 v132, s36, v3
	v_ashrrev_i32_e32 v133, 31, v132
	v_lshlrev_b64 v[132:133], 7, v[132:133]
	v_lshl_add_u64 v[132:133], v[170:171], 0, v[132:133]
	global_load_dwordx4 v[148:151], v[132:133], off
	global_load_dwordx4 v[152:155], v[132:133], off offset:16
	v_add_u32_e32 v132, s25, v3
	v_ashrrev_i32_e32 v133, 31, v132
	v_lshlrev_b64 v[132:133], 7, v[132:133]
	v_lshl_add_u64 v[132:133], v[170:171], 0, v[132:133]
	global_load_dwordx4 v[140:143], v[132:133], off
	global_load_dwordx4 v[144:147], v[132:133], off offset:16
	v_add_u32_e32 v132, s23, v3
	v_ashrrev_i32_e32 v133, 31, v132
	v_lshlrev_b64 v[132:133], 7, v[132:133]
	v_lshl_add_u64 v[136:137], v[170:171], 0, v[132:133]
	global_load_dwordx4 v[132:135], v[136:137], off
	s_nop 0
	global_load_dwordx4 v[136:139], v[136:137], off offset:16
.LBB0_1072:
	s_waitcnt lgkmcnt(0)
	s_and_b64 vcc, exec, s[12:13]
	s_mov_b32 exec_lo, 0xc000c000
	s_mov_b32 exec_hi, 0xc000c000
	ds_read_b128 v[246:249], v234 offset:4608
	ds_read_b128 v[250:253], v234 offset:4624
	s_mov_b64 exec, -1
	v_fma_f32 v68, v194, v12, v226
	v_fma_f32 v69, v195, v13, v227
	v_fma_f32 v70, v196, v14, v228
	v_fma_f32 v71, v197, v15, v229
	v_fma_f32 v64, v198, v4, v230
	v_fma_f32 v65, v199, v5, v231
	v_fma_f32 v66, v200, v6, v232
	v_fma_f32 v67, v201, v7, v233
	v_fmac_f32_dpp v68, v12, v202 row_shr:1 row_mask:0xf bank_mask:0xf
	v_fmac_f32_dpp v69, v13, v203 row_shr:1 row_mask:0xf bank_mask:0xf
	v_fmac_f32_dpp v70, v14, v204 row_shr:1 row_mask:0xf bank_mask:0xf
	v_fmac_f32_dpp v71, v15, v205 row_shr:1 row_mask:0xf bank_mask:0xf
	v_fmac_f32_dpp v64, v4, v206 row_shr:1 row_mask:0xf bank_mask:0xf
	v_fmac_f32_dpp v65, v5, v207 row_shr:1 row_mask:0xf bank_mask:0xf
	v_fmac_f32_dpp v66, v6, v208 row_shr:1 row_mask:0xf bank_mask:0xf
	v_fmac_f32_dpp v67, v7, v209 row_shr:1 row_mask:0xf bank_mask:0xf
	v_fmac_f32_dpp v68, v12, v210 row_shr:2 row_mask:0xf bank_mask:0xf
	v_fmac_f32_dpp v69, v13, v211 row_shr:2 row_mask:0xf bank_mask:0xf
	v_fmac_f32_dpp v70, v14, v212 row_shr:2 row_mask:0xf bank_mask:0xf
	v_fmac_f32_dpp v71, v15, v213 row_shr:2 row_mask:0xf bank_mask:0xf
	v_fmac_f32_dpp v64, v4, v214 row_shr:2 row_mask:0xf bank_mask:0xf
	v_fmac_f32_dpp v65, v5, v215 row_shr:2 row_mask:0xf bank_mask:0xf
	v_fmac_f32_dpp v66, v6, v216 row_shr:2 row_mask:0xf bank_mask:0xf
	v_fmac_f32_dpp v67, v7, v217 row_shr:2 row_mask:0xf bank_mask:0xf
	v_fmac_f32_dpp v68, v20, v202 row_shl:15 row_mask:0xf bank_mask:0xf
	v_fmac_f32_dpp v69, v21, v203 row_shl:15 row_mask:0xf bank_mask:0xf
	v_fmac_f32_dpp v70, v22, v204 row_shl:15 row_mask:0xf bank_mask:0xf
	v_fmac_f32_dpp v71, v23, v205 row_shl:15 row_mask:0xf bank_mask:0xf
	v_fmac_f32_dpp v64, v16, v206 row_shl:15 row_mask:0xf bank_mask:0xf
	v_fmac_f32_dpp v65, v17, v207 row_shl:15 row_mask:0xf bank_mask:0xf
	v_fmac_f32_dpp v66, v18, v208 row_shl:15 row_mask:0xf bank_mask:0xf
	v_fmac_f32_dpp v67, v19, v209 row_shl:15 row_mask:0xf bank_mask:0xf
	v_fmac_f32_dpp v68, v20, v210 row_shl:14 row_mask:0xf bank_mask:0xf
	v_fmac_f32_dpp v69, v21, v211 row_shl:14 row_mask:0xf bank_mask:0xf
	v_fmac_f32_dpp v70, v22, v212 row_shl:14 row_mask:0xf bank_mask:0xf
	v_fmac_f32_dpp v71, v23, v213 row_shl:14 row_mask:0xf bank_mask:0xf
	v_fmac_f32_dpp v64, v16, v214 row_shl:14 row_mask:0xf bank_mask:0xf
	v_fmac_f32_dpp v65, v17, v215 row_shl:14 row_mask:0xf bank_mask:0xf
	v_fmac_f32_dpp v66, v18, v216 row_shl:14 row_mask:0xf bank_mask:0xf
	v_fmac_f32_dpp v67, v19, v217 row_shl:14 row_mask:0xf bank_mask:0xf
	v_fma_f32 v12, v194, v20, v226
	v_fma_f32 v13, v195, v21, v227
	v_fma_f32 v14, v196, v22, v228
	v_fma_f32 v15, v197, v23, v229
	v_fma_f32 v4, v198, v16, v230
	v_fma_f32 v5, v199, v17, v231
	v_fma_f32 v6, v200, v18, v232
	v_fma_f32 v7, v201, v19, v233
	v_fmac_f32_dpp v12, v20, v202 row_shr:1 row_mask:0xf bank_mask:0xf
	v_fmac_f32_dpp v13, v21, v203 row_shr:1 row_mask:0xf bank_mask:0xf
	v_fmac_f32_dpp v14, v22, v204 row_shr:1 row_mask:0xf bank_mask:0xf
	v_fmac_f32_dpp v15, v23, v205 row_shr:1 row_mask:0xf bank_mask:0xf
	v_fmac_f32_dpp v4, v16, v206 row_shr:1 row_mask:0xf bank_mask:0xf
	v_fmac_f32_dpp v5, v17, v207 row_shr:1 row_mask:0xf bank_mask:0xf
	v_fmac_f32_dpp v6, v18, v208 row_shr:1 row_mask:0xf bank_mask:0xf
	v_fmac_f32_dpp v7, v19, v209 row_shr:1 row_mask:0xf bank_mask:0xf
	v_fmac_f32_dpp v12, v20, v210 row_shr:2 row_mask:0xf bank_mask:0xf
	v_fmac_f32_dpp v13, v21, v211 row_shr:2 row_mask:0xf bank_mask:0xf
	v_fmac_f32_dpp v14, v22, v212 row_shr:2 row_mask:0xf bank_mask:0xf
	v_fmac_f32_dpp v15, v23, v213 row_shr:2 row_mask:0xf bank_mask:0xf
	v_fmac_f32_dpp v4, v16, v214 row_shr:2 row_mask:0xf bank_mask:0xf
	v_fmac_f32_dpp v5, v17, v215 row_shr:2 row_mask:0xf bank_mask:0xf
	v_fmac_f32_dpp v6, v18, v216 row_shr:2 row_mask:0xf bank_mask:0xf
	v_fmac_f32_dpp v7, v19, v217 row_shr:2 row_mask:0xf bank_mask:0xf
	v_fmac_f32_dpp v12, v28, v202 row_shl:15 row_mask:0xf bank_mask:0xf
	v_fmac_f32_dpp v13, v29, v203 row_shl:15 row_mask:0xf bank_mask:0xf
	v_fmac_f32_dpp v14, v30, v204 row_shl:15 row_mask:0xf bank_mask:0xf
	v_fmac_f32_dpp v15, v31, v205 row_shl:15 row_mask:0xf bank_mask:0xf
	v_fmac_f32_dpp v4, v24, v206 row_shl:15 row_mask:0xf bank_mask:0xf
	v_fmac_f32_dpp v5, v25, v207 row_shl:15 row_mask:0xf bank_mask:0xf
	v_fmac_f32_dpp v6, v26, v208 row_shl:15 row_mask:0xf bank_mask:0xf
	v_fmac_f32_dpp v7, v27, v209 row_shl:15 row_mask:0xf bank_mask:0xf
	v_fmac_f32_dpp v12, v28, v210 row_shl:14 row_mask:0xf bank_mask:0xf
	v_fmac_f32_dpp v13, v29, v211 row_shl:14 row_mask:0xf bank_mask:0xf
	v_fmac_f32_dpp v14, v30, v212 row_shl:14 row_mask:0xf bank_mask:0xf
	v_fmac_f32_dpp v15, v31, v213 row_shl:14 row_mask:0xf bank_mask:0xf
	v_fmac_f32_dpp v4, v24, v214 row_shl:14 row_mask:0xf bank_mask:0xf
	v_fmac_f32_dpp v5, v25, v215 row_shl:14 row_mask:0xf bank_mask:0xf
	v_fmac_f32_dpp v6, v26, v216 row_shl:14 row_mask:0xf bank_mask:0xf
	v_fmac_f32_dpp v7, v27, v217 row_shl:14 row_mask:0xf bank_mask:0xf
	v_fma_f32 v20, v194, v28, v226
	v_fma_f32 v21, v195, v29, v227
	v_fma_f32 v22, v196, v30, v228
	v_fma_f32 v23, v197, v31, v229
	v_fma_f32 v16, v198, v24, v230
	v_fma_f32 v17, v199, v25, v231
	v_fma_f32 v18, v200, v26, v232
	v_fma_f32 v19, v201, v27, v233
	v_fmac_f32_dpp v20, v28, v202 row_shr:1 row_mask:0xf bank_mask:0xf
	v_fmac_f32_dpp v21, v29, v203 row_shr:1 row_mask:0xf bank_mask:0xf
	v_fmac_f32_dpp v22, v30, v204 row_shr:1 row_mask:0xf bank_mask:0xf
	v_fmac_f32_dpp v23, v31, v205 row_shr:1 row_mask:0xf bank_mask:0xf
	v_fmac_f32_dpp v16, v24, v206 row_shr:1 row_mask:0xf bank_mask:0xf
	v_fmac_f32_dpp v17, v25, v207 row_shr:1 row_mask:0xf bank_mask:0xf
	v_fmac_f32_dpp v18, v26, v208 row_shr:1 row_mask:0xf bank_mask:0xf
	v_fmac_f32_dpp v19, v27, v209 row_shr:1 row_mask:0xf bank_mask:0xf
	v_fmac_f32_dpp v20, v28, v210 row_shr:2 row_mask:0xf bank_mask:0xf
	v_fmac_f32_dpp v21, v29, v211 row_shr:2 row_mask:0xf bank_mask:0xf
	v_fmac_f32_dpp v22, v30, v212 row_shr:2 row_mask:0xf bank_mask:0xf
	v_fmac_f32_dpp v23, v31, v213 row_shr:2 row_mask:0xf bank_mask:0xf
	v_fmac_f32_dpp v16, v24, v214 row_shr:2 row_mask:0xf bank_mask:0xf
	v_fmac_f32_dpp v17, v25, v215 row_shr:2 row_mask:0xf bank_mask:0xf
	v_fmac_f32_dpp v18, v26, v216 row_shr:2 row_mask:0xf bank_mask:0xf
	v_fmac_f32_dpp v19, v27, v217 row_shr:2 row_mask:0xf bank_mask:0xf
	v_fmac_f32_dpp v20, v36, v202 row_shl:15 row_mask:0xf bank_mask:0xf
	v_fmac_f32_dpp v21, v37, v203 row_shl:15 row_mask:0xf bank_mask:0xf
	v_fmac_f32_dpp v22, v38, v204 row_shl:15 row_mask:0xf bank_mask:0xf
	v_fmac_f32_dpp v23, v39, v205 row_shl:15 row_mask:0xf bank_mask:0xf
	v_fmac_f32_dpp v16, v32, v206 row_shl:15 row_mask:0xf bank_mask:0xf
	v_fmac_f32_dpp v17, v33, v207 row_shl:15 row_mask:0xf bank_mask:0xf
	v_fmac_f32_dpp v18, v34, v208 row_shl:15 row_mask:0xf bank_mask:0xf
	v_fmac_f32_dpp v19, v35, v209 row_shl:15 row_mask:0xf bank_mask:0xf
	v_fmac_f32_dpp v20, v36, v210 row_shl:14 row_mask:0xf bank_mask:0xf
	v_fmac_f32_dpp v21, v37, v211 row_shl:14 row_mask:0xf bank_mask:0xf
	v_fmac_f32_dpp v22, v38, v212 row_shl:14 row_mask:0xf bank_mask:0xf
	v_fmac_f32_dpp v23, v39, v213 row_shl:14 row_mask:0xf bank_mask:0xf
	v_fmac_f32_dpp v16, v32, v214 row_shl:14 row_mask:0xf bank_mask:0xf
	v_fmac_f32_dpp v17, v33, v215 row_shl:14 row_mask:0xf bank_mask:0xf
	v_fmac_f32_dpp v18, v34, v216 row_shl:14 row_mask:0xf bank_mask:0xf
	v_fmac_f32_dpp v19, v35, v217 row_shl:14 row_mask:0xf bank_mask:0xf
	s_waitcnt lgkmcnt(0)
	v_fma_f32 v28, v194, v36, v226
	v_fma_f32 v29, v195, v37, v227
	v_fma_f32 v30, v196, v38, v228
	v_fma_f32 v31, v197, v39, v229
	v_fma_f32 v24, v198, v32, v230
	v_fma_f32 v25, v199, v33, v231
	v_fma_f32 v26, v200, v34, v232
	v_fma_f32 v27, v201, v35, v233
	v_fmac_f32_dpp v28, v36, v202 row_shr:1 row_mask:0xf bank_mask:0xf
	v_fmac_f32_dpp v29, v37, v203 row_shr:1 row_mask:0xf bank_mask:0xf
	v_fmac_f32_dpp v30, v38, v204 row_shr:1 row_mask:0xf bank_mask:0xf
	v_fmac_f32_dpp v31, v39, v205 row_shr:1 row_mask:0xf bank_mask:0xf
	v_fmac_f32_dpp v24, v32, v206 row_shr:1 row_mask:0xf bank_mask:0xf
	v_fmac_f32_dpp v25, v33, v207 row_shr:1 row_mask:0xf bank_mask:0xf
	v_fmac_f32_dpp v26, v34, v208 row_shr:1 row_mask:0xf bank_mask:0xf
	v_fmac_f32_dpp v27, v35, v209 row_shr:1 row_mask:0xf bank_mask:0xf
	v_fmac_f32_dpp v28, v36, v210 row_shr:2 row_mask:0xf bank_mask:0xf
	v_fmac_f32_dpp v29, v37, v211 row_shr:2 row_mask:0xf bank_mask:0xf
	v_fmac_f32_dpp v30, v38, v212 row_shr:2 row_mask:0xf bank_mask:0xf
	v_fmac_f32_dpp v31, v39, v213 row_shr:2 row_mask:0xf bank_mask:0xf
	v_fmac_f32_dpp v24, v32, v214 row_shr:2 row_mask:0xf bank_mask:0xf
	v_fmac_f32_dpp v25, v33, v215 row_shr:2 row_mask:0xf bank_mask:0xf
	v_fmac_f32_dpp v26, v34, v216 row_shr:2 row_mask:0xf bank_mask:0xf
	v_fmac_f32_dpp v27, v35, v217 row_shr:2 row_mask:0xf bank_mask:0xf
	v_fmac_f32_dpp v28, v246, v202 row_shl:15 row_mask:0xf bank_mask:0xf
	v_fmac_f32_dpp v29, v247, v203 row_shl:15 row_mask:0xf bank_mask:0xf
	v_fmac_f32_dpp v30, v248, v204 row_shl:15 row_mask:0xf bank_mask:0xf
	v_fmac_f32_dpp v31, v249, v205 row_shl:15 row_mask:0xf bank_mask:0xf
	v_fmac_f32_dpp v24, v250, v206 row_shl:15 row_mask:0xf bank_mask:0xf
	v_fmac_f32_dpp v25, v251, v207 row_shl:15 row_mask:0xf bank_mask:0xf
	v_fmac_f32_dpp v26, v252, v208 row_shl:15 row_mask:0xf bank_mask:0xf
	v_fmac_f32_dpp v27, v253, v209 row_shl:15 row_mask:0xf bank_mask:0xf
	v_fmac_f32_dpp v28, v246, v210 row_shl:14 row_mask:0xf bank_mask:0xf
	v_fmac_f32_dpp v29, v247, v211 row_shl:14 row_mask:0xf bank_mask:0xf
	v_fmac_f32_dpp v30, v248, v212 row_shl:14 row_mask:0xf bank_mask:0xf
	v_fmac_f32_dpp v31, v249, v213 row_shl:14 row_mask:0xf bank_mask:0xf
	v_fmac_f32_dpp v24, v250, v214 row_shl:14 row_mask:0xf bank_mask:0xf
	v_fmac_f32_dpp v25, v251, v215 row_shl:14 row_mask:0xf bank_mask:0xf
	v_fmac_f32_dpp v26, v252, v216 row_shl:14 row_mask:0xf bank_mask:0xf
	v_fmac_f32_dpp v27, v253, v217 row_shl:14 row_mask:0xf bank_mask:0xf
	s_cbranch_vccnz .LBB0_1082
	s_cmp_eq_u32 s24, s66
	s_cbranch_scc1 .LBB0_1082
	s_waitcnt vmcnt(0)
	v_add_f32_e32 v156, v156, v157
	v_add_f32_e32 v157, v158, v159
	v_add_f32_e32 v156, v156, v157
	v_add_f32_e32 v157, v160, v161
	v_add_f32_e32 v158, v162, v163
	v_add_f32_e32 v157, v157, v158
	v_add_f32_e32 v156, v156, v157
	ds_bpermute_b32 v157, v186, v156
	s_waitcnt lgkmcnt(0)
	v_add_f32_e32 v156, v156, v157
	ds_bpermute_b32 v157, v187, v156
	s_and_saveexec_b64 s[34:35], s[6:7]
	s_cbranch_execz .LBB0_1075
	s_waitcnt lgkmcnt(0)
	v_add_f32_e32 v156, v156, v157
	v_fmamk_f32 v156, v156, 0x3a000000, v218
	v_mul_f32_e32 v157, 0x4f800000, v156
	v_cmp_gt_f32_e32 vcc, s49, v156
	s_nop 1
	v_cndmask_b32_e32 v156, v156, v157, vcc
	v_sqrt_f32_e32 v157, v156
	s_nop 0
	v_add_u32_e32 v158, -1, v157
	v_fma_f32 v160, -v158, v157, v156
	v_add_u32_e32 v159, 1, v157
	v_cmp_ge_f32_e64 s[10:11], 0, v160
	s_nop 1
	v_cndmask_b32_e64 v158, v157, v158, s[10:11]
	v_fma_f32 v157, -v159, v157, v156
	v_cmp_lt_f32_e64 s[10:11], 0, v157
	s_nop 1
	v_cndmask_b32_e64 v157, v158, v159, s[10:11]
	v_mul_f32_e32 v158, 0x37800000, v157
	v_cndmask_b32_e32 v157, v157, v158, vcc
	v_cmp_class_f32_e32 vcc, v156, v220
	s_nop 1
	v_cndmask_b32_e32 v156, v157, v156, vcc
	v_div_scale_f32 v157, s[10:11], v156, v156, 1.0
	v_rcp_f32_e32 v158, v157
	s_nop 0
	v_fma_f32 v159, -v157, v158, 1.0
	v_fmac_f32_e32 v158, v159, v158
	v_div_scale_f32 v159, vcc, 1.0, v156, 1.0
	v_mul_f32_e32 v160, v159, v158
	v_fma_f32 v161, -v157, v160, v159
	v_fmac_f32_e32 v160, v161, v158
	v_fma_f32 v157, -v157, v160, v159
	v_div_fmas_f32 v157, v157, v158, v160
	v_div_fixup_f32 v156, v157, v156, 1.0
	ds_write_b32 v193, v156

.LBB0_1082:
	s_add_u32 s10, s42, 0xffffff00
	s_addc_u32 s11, s75, -1
	s_and_b64 vcc, exec, s[12:13]
	s_add_u32 s34, s18, 0x16000000
	s_addc_u32 s35, s19, 0
	v_mul_f32_e32 v246, 0xbfb8aa3b, v176
	v_mul_f32_e32 v247, 0xbfb8aa3b, v177
	v_mul_f32_e32 v248, 0xbfb8aa3b, v178
	v_mul_f32_e32 v249, 0xbfb8aa3b, v179
	v_mul_f32_e32 v250, 0xbfb8aa3b, v182
	v_mul_f32_e32 v251, 0xbfb8aa3b, v183
	v_mul_f32_e32 v252, 0xbfb8aa3b, v184
	v_mul_f32_e32 v253, 0xbfb8aa3b, v185
	v_exp_f32_e32 v246, v246
	v_exp_f32_e32 v247, v247
	v_exp_f32_e32 v248, v248
	v_exp_f32_e32 v249, v249
	v_exp_f32_e32 v250, v250
	v_exp_f32_e32 v251, v251
	v_exp_f32_e32 v252, v252
	v_exp_f32_e32 v253, v253
	v_add_f32_e32 v246, 1.0, v246
	v_add_f32_e32 v247, 1.0, v247
	v_add_f32_e32 v248, 1.0, v248
	v_add_f32_e32 v249, 1.0, v249
	v_add_f32_e32 v250, 1.0, v250
	v_add_f32_e32 v251, 1.0, v251
	v_add_f32_e32 v252, 1.0, v252
	v_add_f32_e32 v253, 1.0, v253
	v_rcp_f32_e32 v246, v246
	v_rcp_f32_e32 v247, v247
	v_rcp_f32_e32 v248, v248
	v_rcp_f32_e32 v249, v249
	v_rcp_f32_e32 v250, v250
	v_rcp_f32_e32 v251, v251
	v_rcp_f32_e32 v252, v252
	v_rcp_f32_e32 v253, v253
	v_mul_f32_e32 v176, v176, v246
	v_mul_f32_e32 v177, v177, v247
	v_mul_f32_e32 v178, v178, v248
	v_mul_f32_e32 v179, v179, v249
	v_mul_f32_e32 v182, v182, v250
	v_mul_f32_e32 v183, v183, v251
	v_mul_f32_e32 v184, v184, v252
	v_mul_f32_e32 v185, v185, v253
	v_mul_f32_e32 v176, v176, v68
	v_mul_f32_e32 v177, v177, v69
	v_mul_f32_e32 v178, v178, v70
	v_mul_f32_e32 v179, v179, v71
	v_mul_f32_e32 v182, v182, v64
	v_mul_f32_e32 v183, v183, v65
	v_mul_f32_e32 v184, v184, v66
	v_mul_f32_e32 v185, v185, v67
	v_cvt_pk_bf16_f32 v176, v176, v177
	v_cvt_pk_bf16_f32 v177, v178, v179
	v_cvt_pk_bf16_f32 v178, v182, v183
	v_cvt_pk_bf16_f32 v179, v184, v185
	v_add_u32_e32 v221, 0x1e4000, v245
	global_store_dwordx4 v221, v[176:179], s[34:35]
	v_mul_f32_e32 v246, 0xbfb8aa3b, v44
	v_mul_f32_e32 v247, 0xbfb8aa3b, v45
	v_mul_f32_e32 v248, 0xbfb8aa3b, v46
	v_mul_f32_e32 v249, 0xbfb8aa3b, v47
	v_mul_f32_e32 v250, 0xbfb8aa3b, v40
	v_mul_f32_e32 v251, 0xbfb8aa3b, v41
	v_mul_f32_e32 v252, 0xbfb8aa3b, v42
	v_mul_f32_e32 v253, 0xbfb8aa3b, v43
	v_exp_f32_e32 v246, v246
	v_exp_f32_e32 v247, v247
	v_exp_f32_e32 v248, v248
	v_exp_f32_e32 v249, v249
	v_exp_f32_e32 v250, v250
	v_exp_f32_e32 v251, v251
	v_exp_f32_e32 v252, v252
	v_exp_f32_e32 v253, v253
	v_add_f32_e32 v246, 1.0, v246
	v_add_f32_e32 v247, 1.0, v247
	v_add_f32_e32 v248, 1.0, v248
	v_add_f32_e32 v249, 1.0, v249
	v_add_f32_e32 v250, 1.0, v250
	v_add_f32_e32 v251, 1.0, v251
	v_add_f32_e32 v252, 1.0, v252
	v_add_f32_e32 v253, 1.0, v253
	v_rcp_f32_e32 v246, v246
	v_rcp_f32_e32 v247, v247
	v_rcp_f32_e32 v248, v248
	v_rcp_f32_e32 v249, v249
	v_rcp_f32_e32 v250, v250
	v_rcp_f32_e32 v251, v251
	v_rcp_f32_e32 v252, v252
	v_rcp_f32_e32 v253, v253
	v_mul_f32_e32 v44, v44, v246
	v_mul_f32_e32 v45, v45, v247
	v_mul_f32_e32 v46, v46, v248
	v_mul_f32_e32 v47, v47, v249
	v_mul_f32_e32 v40, v40, v250
	v_mul_f32_e32 v41, v41, v251
	v_mul_f32_e32 v42, v42, v252
	v_mul_f32_e32 v43, v43, v253
	v_mul_f32_e32 v44, v44, v12
	v_mul_f32_e32 v45, v45, v13
	v_mul_f32_e32 v46, v46, v14
	v_mul_f32_e32 v47, v47, v15
	v_mul_f32_e32 v40, v40, v4
	v_mul_f32_e32 v41, v41, v5
	v_mul_f32_e32 v42, v42, v6
	v_mul_f32_e32 v43, v43, v7
	v_cvt_pk_bf16_f32 v44, v44, v45
	v_cvt_pk_bf16_f32 v45, v46, v47
	v_cvt_pk_bf16_f32 v46, v40, v41
	v_cvt_pk_bf16_f32 v47, v42, v43
	v_add_u32_e32 v240, 0x1b8000, v245
	global_store_dwordx4 v240, v[44:47], s[34:35]
	v_mul_f32_e32 v246, 0xbfb8aa3b, v52
	v_mul_f32_e32 v247, 0xbfb8aa3b, v53
	v_mul_f32_e32 v248, 0xbfb8aa3b, v54
	v_mul_f32_e32 v249, 0xbfb8aa3b, v55
	v_mul_f32_e32 v250, 0xbfb8aa3b, v48
	v_mul_f32_e32 v251, 0xbfb8aa3b, v49
	v_mul_f32_e32 v252, 0xbfb8aa3b, v50
	v_mul_f32_e32 v253, 0xbfb8aa3b, v51
	v_exp_f32_e32 v246, v246
	v_exp_f32_e32 v247, v247
	v_exp_f32_e32 v248, v248
	v_exp_f32_e32 v249, v249
	v_exp_f32_e32 v250, v250
	v_exp_f32_e32 v251, v251
	v_exp_f32_e32 v252, v252
	v_exp_f32_e32 v253, v253
	v_add_f32_e32 v246, 1.0, v246
	v_add_f32_e32 v247, 1.0, v247
	v_add_f32_e32 v248, 1.0, v248
	v_add_f32_e32 v249, 1.0, v249
	v_add_f32_e32 v250, 1.0, v250
	v_add_f32_e32 v251, 1.0, v251
	v_add_f32_e32 v252, 1.0, v252
	v_add_f32_e32 v253, 1.0, v253
	v_rcp_f32_e32 v246, v246
	v_rcp_f32_e32 v247, v247
	v_rcp_f32_e32 v248, v248
	v_rcp_f32_e32 v249, v249
	v_rcp_f32_e32 v250, v250
	v_rcp_f32_e32 v251, v251
	v_rcp_f32_e32 v252, v252
	v_rcp_f32_e32 v253, v253
	v_mul_f32_e32 v52, v52, v246
	v_mul_f32_e32 v53, v53, v247
	v_mul_f32_e32 v54, v54, v248
	v_mul_f32_e32 v55, v55, v249
	v_mul_f32_e32 v48, v48, v250
	v_mul_f32_e32 v49, v49, v251
	v_mul_f32_e32 v50, v50, v252
	v_mul_f32_e32 v51, v51, v253
	v_mul_f32_e32 v52, v52, v20
	v_mul_f32_e32 v53, v53, v21
	v_mul_f32_e32 v54, v54, v22
	v_mul_f32_e32 v55, v55, v23
	v_mul_f32_e32 v48, v48, v16
	v_mul_f32_e32 v49, v49, v17
	v_mul_f32_e32 v50, v50, v18
	v_mul_f32_e32 v51, v51, v19
	v_cvt_pk_bf16_f32 v52, v52, v53
	v_cvt_pk_bf16_f32 v53, v54, v55
	v_cvt_pk_bf16_f32 v54, v48, v49
	v_cvt_pk_bf16_f32 v55, v50, v51
	v_add_u32_e32 v221, 0x18c000, v245
	global_store_dwordx4 v221, v[52:55], s[34:35]
	v_mul_f32_e32 v246, 0xbfb8aa3b, v60
	v_mul_f32_e32 v247, 0xbfb8aa3b, v61
	v_mul_f32_e32 v248, 0xbfb8aa3b, v62
	v_mul_f32_e32 v249, 0xbfb8aa3b, v63
	v_mul_f32_e32 v250, 0xbfb8aa3b, v56
	v_mul_f32_e32 v251, 0xbfb8aa3b, v57
	v_mul_f32_e32 v252, 0xbfb8aa3b, v58
	v_mul_f32_e32 v253, 0xbfb8aa3b, v59
	v_exp_f32_e32 v246, v246
	v_exp_f32_e32 v247, v247
	v_exp_f32_e32 v248, v248
	v_exp_f32_e32 v249, v249
	v_exp_f32_e32 v250, v250
	v_exp_f32_e32 v251, v251
	v_exp_f32_e32 v252, v252
	v_exp_f32_e32 v253, v253
	v_add_f32_e32 v246, 1.0, v246
	v_add_f32_e32 v247, 1.0, v247
	v_add_f32_e32 v248, 1.0, v248
	v_add_f32_e32 v249, 1.0, v249
	v_add_f32_e32 v250, 1.0, v250
	v_add_f32_e32 v251, 1.0, v251
	v_add_f32_e32 v252, 1.0, v252
	v_add_f32_e32 v253, 1.0, v253
	v_rcp_f32_e32 v246, v246
	v_rcp_f32_e32 v247, v247
	v_rcp_f32_e32 v248, v248
	v_rcp_f32_e32 v249, v249
	v_rcp_f32_e32 v250, v250
	v_rcp_f32_e32 v251, v251
	v_rcp_f32_e32 v252, v252
	v_rcp_f32_e32 v253, v253
	v_mul_f32_e32 v60, v60, v246
	v_mul_f32_e32 v61, v61, v247
	v_mul_f32_e32 v62, v62, v248
	v_mul_f32_e32 v63, v63, v249
	v_mul_f32_e32 v56, v56, v250
	v_mul_f32_e32 v57, v57, v251
	v_mul_f32_e32 v58, v58, v252
	v_mul_f32_e32 v59, v59, v253
	v_mul_f32_e32 v60, v60, v28
	v_mul_f32_e32 v61, v61, v29
	v_mul_f32_e32 v62, v62, v30
	v_mul_f32_e32 v63, v63, v31
	v_mul_f32_e32 v56, v56, v24
	v_mul_f32_e32 v57, v57, v25
	v_mul_f32_e32 v58, v58, v26
	v_mul_f32_e32 v59, v59, v27
	v_cvt_pk_bf16_f32 v60, v60, v61
	v_cvt_pk_bf16_f32 v61, v62, v63
	v_cvt_pk_bf16_f32 v62, v56, v57
	v_cvt_pk_bf16_f32 v63, v58, v59
	v_add_u32_e32 v240, 0x160000, v245
	global_store_dwordx4 v240, v[60:63], s[34:35]
	s_cbranch_vccnz .LBB0_1093
	s_cmp_eq_u32 s24, s66
	s_cbranch_scc1 .LBB0_1091
	s_waitcnt vmcnt(0)
	v_add_f32_e32 v4, v156, v157
	v_add_f32_e32 v5, v158, v159
	v_add_f32_e32 v4, v4, v5
	v_add_f32_e32 v5, v160, v161
	v_add_f32_e32 v6, v162, v163
	v_add_f32_e32 v5, v5, v6
	v_add_f32_e32 v4, v4, v5
	ds_bpermute_b32 v5, v186, v4
	s_waitcnt lgkmcnt(0)
	v_add_f32_e32 v4, v4, v5
	ds_bpermute_b32 v5, v187, v4
	s_and_saveexec_b64 s[12:13], s[6:7]
	s_cbranch_execz .LBB0_1085
	s_waitcnt lgkmcnt(0)
	v_add_f32_e32 v4, v4, v5
	v_fmamk_f32 v4, v4, 0x3a000000, v218
	v_mul_f32_e32 v5, 0x4f800000, v4
	v_cmp_gt_f32_e32 vcc, s49, v4
	s_nop 1
	v_cndmask_b32_e32 v4, v4, v5, vcc
	v_sqrt_f32_e32 v5, v4
	s_nop 0
	v_add_u32_e32 v6, -1, v5
	v_fma_f32 v8, -v6, v5, v4
	v_add_u32_e32 v7, 1, v5
	v_cmp_ge_f32_e64 s[10:11], 0, v8
	s_nop 1
	v_cndmask_b32_e64 v6, v5, v6, s[10:11]
	v_fma_f32 v5, -v7, v5, v4
	v_cmp_lt_f32_e64 s[10:11], 0, v5
	s_nop 1
	v_cndmask_b32_e64 v5, v6, v7, s[10:11]
	v_mul_f32_e32 v6, 0x37800000, v5
	v_cndmask_b32_e32 v5, v5, v6, vcc
	v_cmp_class_f32_e32 vcc, v4, v220
	s_nop 1
	v_cndmask_b32_e32 v4, v5, v4, vcc
	v_div_scale_f32 v5, s[10:11], v4, v4, 1.0
	v_rcp_f32_e32 v6, v5
	s_nop 0
	v_fma_f32 v7, -v5, v6, 1.0
	v_fmac_f32_e32 v6, v7, v6
	v_div_scale_f32 v7, vcc, 1.0, v4, 1.0
	v_mul_f32_e32 v8, v7, v6
	v_fma_f32 v9, -v5, v8, v7
	v_fmac_f32_e32 v8, v9, v6
	v_fma_f32 v5, -v5, v8, v7
	v_div_fmas_f32 v5, v5, v6, v8
	v_div_fixup_f32 v4, v5, v4, 1.0
	ds_write_b32 v193, v4 offset:256
